# v15: v8 + all GEMM K-loop LDS-DMA loads in SGPR-base form (192 of 220 sites), no per-load 64-bit VALU address add
# speedup vs baseline: 1.0115x; 1.0004x over previous
; #define PG8_WAIT_V(n) asm volatile("s_waitcnt vmcnt(" #n ")" ::: "memory")
; #define PG8_BAR __builtin_amdgcn_s_barrier()
;     ...
;     const int aoff = lds_byte(wr * 64 + fr, fq * 8), boff = lds_byte(wc * 32 + fr, fq * 8);
;     ...
;         PG8_STAGE(PG8_SB(0, 0), cB, voffB); PG8_STAGE(PG8_SB(0, 1), cB + hstep, voffB); PG8_STAGE(PG8_SA(0, 0), cA, voffA); PG8_STAGE(PG8_SA(0, 1), cA + hstepA, voffA);
;         if (wr == 1) PG8_BAR;
;         PG8_WAIT_V(2); PG8_BAR;
;         PG8_STAGE(PG8_SB(1, 0), cB + kstep, voffB); PG8_STAGE(PG8_SA(1, 0), cA + kstep, voffA); PG8_STAGE(PG8_SB(1, 1), cB + hstep + kstep, voffB);
;         PG8_WAIT_V(6); PG8_BAR;
.LBB0_1194:
	v_readlane_b32 s28, v254, 11
	v_readlane_b32 s30, v254, 13
	v_readlane_b32 s29, v254, 12
	v_readlane_b32 s31, v254, 14
	s_and_b32 s5, s5, 3
	s_and_b32 s85, s93, 0xffff
	s_and_b32 s21, s59, 0xffff
	s_and_b32 s25, s60, 0xffff
	s_and_b32 s13, s29, 0xffff
	s_and_b32 s29, s31, 0xffff
	s_lshl_b32 s66, s12, 6
	s_lshl_b32 s7, s12, 13
	s_lshl_b32 s67, s5, 5
	s_lshl_b32 s9, s5, 12
	s_waitcnt lgkmcnt(0)
	s_add_u32 s14, s26, 0x80
	s_addc_u32 s15, s27, 0
	s_add_i32 m0, s57, 0x18000
	s_waitcnt vmcnt(2)
	s_barrier
	global_load_lds_dwordx4 v138, s[14:15]
	s_add_i32 m0, s57, 0x1a000
	v_lshl_add_u64 v[2:3], s[14:15], 0, v[142:143]
	s_add_u32 s14, s10, 0x80
	s_addc_u32 s15, s11, 0
	s_add_i32 s68, s57, 0x8000
	global_load_lds_dwordx4 v[2:3], off
	s_mov_b32 m0, s68
	s_add_i32 s69, s57, 0xa000
	global_load_lds_dwordx4 v136, s[14:15]
	v_lshl_add_u64 v[2:3], s[14:15], 0, v[140:141]
	s_add_u32 s14, s26, 0x80080
	s_mov_b32 m0, s69
	s_addc_u32 s15, s27, 0
	global_load_lds_dwordx4 v[2:3], off
	s_add_i32 m0, s57, 0x1c000
	global_load_lds_dwordx4 v138, s[14:15]
	s_add_i32 m0, s57, 0x1e000
	s_mov_b32 s12, s28
	global_load_lds_dwordx4 v142, s[14:15]
	s_mov_b32 s28, s30
	v_and_b32_e32 v1, 48, v0
	v_lshlrev_b32_e32 v2, 6, v0
	s_movk_i32 s30, 0x3c0
	v_lshlrev_b32_e32 v0, 2, v0
	v_and_or_b32 v1, v2, s30, v1
	v_and_b32_e32 v0, 32, v0
	s_waitcnt vmcnt(6)
	s_cmpk_lt_u32 s4, 0x100
	s_mov_b32 s87, 0x20000
	v_bitop3_b32 v2, v1, s7, v0 bitop3:0xde
	v_bitop3_b32 v148, s9, v1, v0 bitop3:0xf6
	s_cselect_b64 s[36:37], -1, 0
	s_add_i32 s71, 0, 0x10000
	s_add_i32 s72, 0, 0x14000
	s_brev_b32 s86, 16
	s_brev_b32 s22, 64
	s_mov_b32 s23, s87
	s_mov_b32 s14, 0x400000
	s_mov_b32 s15, s87
	s_lshl_b32 s70, s5, 6
	v_add_u32_e32 v149, s71, v148
	v_add_u32_e32 v150, s72, v148
	v_add_u32_e32 v151, 0, v2
	v_mov_b32_e32 v152, 0x7f7f7f7f
	s_mov_b32 s38, 0x3c800000
	s_mov_b32 s73, 0x200000
	s_barrier
	s_branch .LBB0_1197

; #define PG8_WAIT_V(n) asm volatile("s_waitcnt vmcnt(" #n ")" ::: "memory")
; #define PG8_WAIT_L(n) asm volatile("s_waitcnt lgkmcnt(" #n ")" ::: "memory")
; #define PG8_BAR __builtin_amdgcn_s_barrier()
; #define PG8_SCHED __builtin_amdgcn_sched_barrier(0)
;     ...
;             PG8_LDB(B0, 0, 0); PG8_LDB(B1, 0, 1); PG8_SCHED; PG8_LDA(At, 0, 0); PG8_STAGE(PG8_SA(1, 1), a1 + hstepA, voffA);
;             PG8_WAIT_V(8); PG8_WAIT_L(0); PG8_BAR; PG8_MMA(0, 0, At, B0); PG8_MMA(0, 1, At, B1); PG8_BAR; PG8_SCHED;
;             if constexpr (!HALFU) PG8_LDA(At, 0, 1); PG8_STAGE(PG8_SB(0, 0), b2, voffB); PG8_STAGE(PG8_SB(0, 1), b2 + hstep, voffB); PG8_STAGE(PG8_SA(0, 0), a2, voffA);
;             PG8_WAIT_V(8); PG8_WAIT_L(0); PG8_BAR; if constexpr (!HALFU) { PG8_MMA(1, 0, At, B0); PG8_MMA(1, 1, At, B1); } PG8_BAR; PG8_SCHED;
.LBB0_1200:
	ds_read_b128 v[128:131], v149
	ds_read_b128 v[132:135], v149 offset:1024
	ds_read_b128 v[154:157], v149 offset:2048
	ds_read_b128 v[158:161], v149 offset:3072
	ds_read_b128 v[162:165], v150
	ds_read_b128 v[166:169], v150 offset:1024
	ds_read_b128 v[170:173], v150 offset:2048
	ds_read_b128 v[174:177], v150 offset:3072
	s_add_u32 s26, s10, 0x100
	s_addc_u32 s27, s11, 0
	s_cmp_eq_u32 s76, 28
	s_cselect_b32 s50, s9, s26
	s_cselect_b32 s51, s7, s27
	s_cselect_b32 s48, s43, s74
	s_cselect_b32 s49, s41, s75
	s_add_u32 s30, s50, 0x80
	s_addc_u32 s31, s51, 0
	s_add_u32 s10, s10, 0x80080
	s_addc_u32 s11, s11, 0
	s_add_i32 m0, s57, 0xc000
	ds_read_b128 v[178:181], v151
	ds_read_b128 v[182:185], v151 offset:1024
	ds_read_b128 v[186:189], v151 offset:2048
	ds_read_b128 v[190:193], v151 offset:3072
	ds_read_b128 v[194:197], v151 offset:4096
	ds_read_b128 v[198:201], v151 offset:5120
	ds_read_b128 v[202:205], v151 offset:6144
	ds_read_b128 v[206:209], v151 offset:7168
	global_load_lds_dwordx4 v136, s[10:11]
	s_add_i32 m0, s57, 0xe000
	s_nop 0
	global_load_lds_dwordx4 v140, s[10:11]
	s_waitcnt vmcnt(8)
	s_waitcnt lgkmcnt(0)
	s_barrier
	s_setprio 1
	s_waitcnt lgkmcnt(0)
	v_mfma_scale_f32_16x16x128_f8f6f4 v[124:127], v[128:135], v[178:185], v[124:127], v152, v152 op_sel_hi:[0,0,0]
	v_mfma_scale_f32_16x16x128_f8f6f4 v[120:123], v[154:161], v[178:185], v[120:123], v152, v152 op_sel_hi:[0,0,0]
	v_mfma_scale_f32_16x16x128_f8f6f4 v[108:111], v[128:135], v[186:193], v[108:111], v152, v152 op_sel_hi:[0,0,0]
	v_mfma_scale_f32_16x16x128_f8f6f4 v[104:107], v[154:161], v[186:193], v[104:107], v152, v152 op_sel_hi:[0,0,0]
	v_mfma_scale_f32_16x16x128_f8f6f4 v[210:213], v[128:135], v[194:201], v[92:95], v152, v152 op_sel_hi:[0,0,0]
	v_mfma_scale_f32_16x16x128_f8f6f4 v[214:217], v[154:161], v[194:201], v[88:91], v152, v152 op_sel_hi:[0,0,0]
	v_mfma_scale_f32_16x16x128_f8f6f4 v[218:221], v[128:135], v[202:209], v[76:79], v152, v152 op_sel_hi:[0,0,0]
	v_mfma_scale_f32_16x16x128_f8f6f4 v[222:225], v[154:161], v[202:209], v[72:75], v152, v152 op_sel_hi:[0,0,0]
	s_setprio 0
	s_setprio 1
	v_mfma_scale_f32_16x16x128_f8f6f4 v[116:119], v[162:169], v[178:185], v[116:119], v152, v152 op_sel_hi:[0,0,0]
	v_mfma_scale_f32_16x16x128_f8f6f4 v[112:115], v[170:177], v[178:185], v[112:115], v152, v152 op_sel_hi:[0,0,0]
	v_mfma_scale_f32_16x16x128_f8f6f4 v[100:103], v[162:169], v[186:193], v[100:103], v152, v152 op_sel_hi:[0,0,0]
	v_mfma_scale_f32_16x16x128_f8f6f4 v[96:99], v[170:177], v[186:193], v[96:99], v152, v152 op_sel_hi:[0,0,0]
	v_mfma_scale_f32_16x16x128_f8f6f4 v[178:181], v[162:169], v[194:201], v[84:87], v152, v152 op_sel_hi:[0,0,0]
	v_mfma_scale_f32_16x16x128_f8f6f4 v[182:185], v[170:177], v[194:201], v[80:83], v152, v152 op_sel_hi:[0,0,0]
	v_mfma_scale_f32_16x16x128_f8f6f4 v[186:189], v[162:169], v[202:209], v[68:71], v152, v152 op_sel_hi:[0,0,0]
	v_mfma_scale_f32_16x16x128_f8f6f4 v[190:193], v[170:177], v[202:209], v[64:67], v152, v152 op_sel_hi:[0,0,0]
	s_setprio 0
	s_barrier
	s_add_i32 s10, s71, s56
	s_mov_b32 m0, s10
	s_nop 1
	ds_read_b128 v[64:67], v151 offset:16384
	ds_read_b128 v[68:71], v151 offset:17408
	ds_read_b128 v[72:75], v151 offset:18432
	ds_read_b128 v[76:79], v151 offset:19456
	ds_read_b128 v[80:83], v151 offset:20480
	ds_read_b128 v[84:87], v151 offset:21504
	ds_read_b128 v[88:91], v151 offset:22528
	ds_read_b128 v[92:95], v151 offset:23552
	global_load_lds_dwordx4 v138, s[48:49]
	s_add_i32 m0, s10, 0x2000
	s_add_u32 s10, s48, 0x80000
	s_addc_u32 s11, s49, 0
	s_add_i32 s77, s72, s56
	global_load_lds_dwordx4 v142, s[48:49]
	s_mov_b32 m0, s77
	s_nop 0
	global_load_lds_dwordx4 v138, s[10:11]
	s_add_i32 m0, s77, 0x2000
	s_nop 0
	global_load_lds_dwordx4 v142, s[10:11]
	s_mov_b32 m0, s57
	s_nop 0
	global_load_lds_dwordx4 v136, s[50:51]
	s_mov_b32 m0, s62
	s_nop 0
	global_load_lds_dwordx4 v140, s[50:51]
	s_waitcnt vmcnt(8)
	s_waitcnt lgkmcnt(0)
	s_barrier
	s_setprio 1
	s_waitcnt lgkmcnt(0)
	v_mfma_scale_f32_16x16x128_f8f6f4 v[60:63], v[128:135], v[64:71], v[60:63], v152, v152 op_sel_hi:[0,0,0]
	v_mfma_scale_f32_16x16x128_f8f6f4 v[56:59], v[154:161], v[64:71], v[56:59], v152, v152 op_sel_hi:[0,0,0]
	v_mfma_scale_f32_16x16x128_f8f6f4 v[194:197], v[128:135], v[72:79], v[44:47], v152, v152 op_sel_hi:[0,0,0]
	v_mfma_scale_f32_16x16x128_f8f6f4 v[198:201], v[154:161], v[72:79], v[40:43], v152, v152 op_sel_hi:[0,0,0]
	v_mfma_scale_f32_16x16x128_f8f6f4 v[202:205], v[128:135], v[80:87], v[28:31], v152, v152 op_sel_hi:[0,0,0]
	v_mfma_scale_f32_16x16x128_f8f6f4 v[206:209], v[154:161], v[80:87], v[24:27], v152, v152 op_sel_hi:[0,0,0]
	v_mfma_scale_f32_16x16x128_f8f6f4 v[226:229], v[128:135], v[88:95], v[12:15], v152, v152 op_sel_hi:[0,0,0]
	v_mfma_scale_f32_16x16x128_f8f6f4 v[230:233], v[154:161], v[88:95], v[8:11], v152, v152 op_sel_hi:[0,0,0]
	s_setprio 0
	s_setprio 1
	v_mfma_scale_f32_16x16x128_f8f6f4 v[52:55], v[162:169], v[64:71], v[52:55], v152, v152 op_sel_hi:[0,0,0]
	v_mfma_scale_f32_16x16x128_f8f6f4 v[48:51], v[170:177], v[64:71], v[48:51], v152, v152 op_sel_hi:[0,0,0]
	v_mfma_scale_f32_16x16x128_f8f6f4 v[234:237], v[162:169], v[72:79], v[36:39], v152, v152 op_sel_hi:[0,0,0]
	v_mfma_scale_f32_16x16x128_f8f6f4 v[238:241], v[170:177], v[72:79], v[32:35], v152, v152 op_sel_hi:[0,0,0]
	v_mfma_scale_f32_16x16x128_f8f6f4 v[242:245], v[162:169], v[80:87], v[20:23], v152, v152 op_sel_hi:[0,0,0]
	v_mfma_scale_f32_16x16x128_f8f6f4 v[246:249], v[170:177], v[80:87], v[16:19], v152, v152 op_sel_hi:[0,0,0]
	v_mfma_scale_f32_16x16x128_f8f6f4 v[250:253], v[162:169], v[88:95], v[4:7], v152, v152 op_sel_hi:[0,0,0]
	v_mfma_scale_f32_16x16x128_f8f6f4 v[144:147], v[170:177], v[88:95], v[0:3], v152, v152 op_sel_hi:[0,0,0]
	s_setprio 0
	s_barrier
; #define PG8_WAIT_V(n) asm volatile("s_waitcnt vmcnt(" #n ")" ::: "memory")
; #define PG8_WAIT_L(n) asm volatile("s_waitcnt lgkmcnt(" #n ")" ::: "memory")
; #define PG8_BAR __builtin_amdgcn_s_barrier()
; #define PG8_SCHED __builtin_amdgcn_sched_barrier(0)
;     ...
;         for (int t = 0; t < nt; t += 2) {
;             const bool last = (t == nt - 2);
;             const char* a1 = cA + (size_t)(t + 1) * kstep;
;             const char* a2 = last ? nA : cA + (size_t)(t + 2) * kstep; const char* b2 = last ? nB : cB + (size_t)(t + 2) * kstep;
;             const char* a3 = a2 + kstep; const char* b3 = b2 + kstep;
;     ...
;             PG8_LDB(B0, 1, 0); PG8_LDB(B1, 1, 1); PG8_SCHED; PG8_LDA(At, 1, 0); PG8_STAGE(PG8_SA(0, 1), a2 + hstepA, voffA);
;             PG8_WAIT_V(8); PG8_WAIT_L(0); PG8_BAR; PG8_MMA(0, 0, At, B0); PG8_MMA(0, 1, At, B1); PG8_BAR; PG8_SCHED;
;             if constexpr (!HALFU) PG8_LDA(At, 1, 1); PG8_STAGE(PG8_SB(1, 0), b3, voffB); PG8_STAGE(PG8_SB(1, 1), b3 + hstep, voffB); PG8_STAGE(PG8_SA(1, 0), a3, voffA);
;             PG8_WAIT_V(8); PG8_WAIT_L(0); PG8_BAR; if constexpr (!HALFU) { PG8_MMA(1, 0, At, B0); PG8_MMA(1, 1, At, B1); } PG8_BAR; PG8_SCHED;
	s_add_i32 s77, 0, 0x18000
	v_add_u32_e32 v8, s77, v148
	s_add_i32 s78, 0, 0x1c000
	s_nop 1
	ds_read_b128 v[0:3], v8
	ds_read_b128 v[4:7], v8 offset:1024
	ds_read_b128 v[16:19], v8 offset:2048
	ds_read_b128 v[20:23], v8 offset:3072
	v_add_u32_e32 v8, s78, v148
	ds_read_b128 v[128:131], v8
	ds_read_b128 v[132:135], v8 offset:1024
	ds_read_b128 v[154:157], v8 offset:2048
	ds_read_b128 v[158:161], v8 offset:3072
	s_add_u32 s10, s50, 0x80000
	s_addc_u32 s11, s51, 0
	s_mov_b32 m0, s63
	ds_read_b128 v[8:11], v151 offset:32768
	ds_read_b128 v[12:15], v151 offset:33792
	ds_read_b128 v[24:27], v151 offset:34816
	ds_read_b128 v[28:31], v151 offset:35840
	ds_read_b128 v[32:35], v151 offset:36864
	ds_read_b128 v[36:39], v151 offset:37888
	ds_read_b128 v[40:43], v151 offset:38912
	ds_read_b128 v[44:47], v151 offset:39936
	global_load_lds_dwordx4 v136, s[10:11]
	s_mov_b32 m0, s64
	s_nop 0
	global_load_lds_dwordx4 v140, s[10:11]
	s_waitcnt vmcnt(8)
	s_waitcnt lgkmcnt(0)
	s_barrier
	s_setprio 1
	s_waitcnt lgkmcnt(0)
	v_mfma_scale_f32_16x16x128_f8f6f4 v[124:127], v[0:7], v[8:15], v[124:127], v152, v152 op_sel_hi:[0,0,0]
	v_mfma_scale_f32_16x16x128_f8f6f4 v[120:123], v[16:23], v[8:15], v[120:123], v152, v152 op_sel_hi:[0,0,0]
	v_mfma_scale_f32_16x16x128_f8f6f4 v[108:111], v[0:7], v[24:31], v[108:111], v152, v152 op_sel_hi:[0,0,0]
	v_mfma_scale_f32_16x16x128_f8f6f4 v[104:107], v[16:23], v[24:31], v[104:107], v152, v152 op_sel_hi:[0,0,0]
	v_mfma_scale_f32_16x16x128_f8f6f4 v[92:95], v[0:7], v[32:39], v[210:213], v152, v152 op_sel_hi:[0,0,0]
	v_mfma_scale_f32_16x16x128_f8f6f4 v[88:91], v[16:23], v[32:39], v[214:217], v152, v152 op_sel_hi:[0,0,0]
	v_mfma_scale_f32_16x16x128_f8f6f4 v[76:79], v[0:7], v[40:47], v[218:221], v152, v152 op_sel_hi:[0,0,0]
	v_mfma_scale_f32_16x16x128_f8f6f4 v[72:75], v[16:23], v[40:47], v[222:225], v152, v152 op_sel_hi:[0,0,0]
	s_setprio 0
	s_setprio 1
	v_mfma_scale_f32_16x16x128_f8f6f4 v[116:119], v[128:135], v[8:15], v[116:119], v152, v152 op_sel_hi:[0,0,0]
	v_mfma_scale_f32_16x16x128_f8f6f4 v[112:115], v[154:161], v[8:15], v[112:115], v152, v152 op_sel_hi:[0,0,0]
	v_mfma_scale_f32_16x16x128_f8f6f4 v[100:103], v[128:135], v[24:31], v[100:103], v152, v152 op_sel_hi:[0,0,0]
	v_mfma_scale_f32_16x16x128_f8f6f4 v[96:99], v[154:161], v[24:31], v[96:99], v152, v152 op_sel_hi:[0,0,0]
	v_mfma_scale_f32_16x16x128_f8f6f4 v[84:87], v[128:135], v[32:39], v[178:181], v152, v152 op_sel_hi:[0,0,0]
	v_mfma_scale_f32_16x16x128_f8f6f4 v[80:83], v[154:161], v[32:39], v[182:185], v152, v152 op_sel_hi:[0,0,0]
	v_mfma_scale_f32_16x16x128_f8f6f4 v[68:71], v[128:135], v[40:47], v[186:189], v152, v152 op_sel_hi:[0,0,0]
	v_mfma_scale_f32_16x16x128_f8f6f4 v[64:67], v[154:161], v[40:47], v[190:193], v152, v152 op_sel_hi:[0,0,0]
	s_setprio 0
	s_barrier
	s_add_u32 s10, s48, 0x80
	s_addc_u32 s11, s49, 0
	s_add_i32 s50, s77, s56
	s_mov_b32 m0, s50
	ds_read_b128 v[32:35], v151 offset:49152
	ds_read_b128 v[36:39], v151 offset:50176
	ds_read_b128 v[162:165], v151 offset:51200
	ds_read_b128 v[166:169], v151 offset:52224
	ds_read_b128 v[170:173], v151 offset:53248
	ds_read_b128 v[174:177], v151 offset:54272
	ds_read_b128 v[178:181], v151 offset:55296
	ds_read_b128 v[182:185], v151 offset:56320
	global_load_lds_dwordx4 v138, s[10:11]
	s_add_i32 m0, s50, 0x2000
	v_lshl_add_u64 v[8:9], s[10:11], 0, v[142:143]
	s_add_u32 s10, s48, 0x80080
	s_addc_u32 s11, s49, 0
	s_add_i32 s48, s78, s56
	global_load_lds_dwordx4 v[8:9], off
	s_mov_b32 m0, s48
	s_nop 0
	global_load_lds_dwordx4 v138, s[10:11]
	s_add_i32 m0, s48, 0x2000
	s_nop 0
	global_load_lds_dwordx4 v142, s[10:11]
	s_mov_b32 m0, s68
	s_nop 0
	global_load_lds_dwordx4 v136, s[30:31]
	s_mov_b32 m0, s69
	s_nop 0
	global_load_lds_dwordx4 v140, s[30:31]
	s_waitcnt vmcnt(8)
	s_waitcnt lgkmcnt(0)
	s_barrier
	s_setprio 1
	s_waitcnt lgkmcnt(0)
	v_mfma_scale_f32_16x16x128_f8f6f4 v[60:63], v[0:7], v[32:39], v[60:63], v152, v152 op_sel_hi:[0,0,0]
	v_mfma_scale_f32_16x16x128_f8f6f4 v[56:59], v[16:23], v[32:39], v[56:59], v152, v152 op_sel_hi:[0,0,0]
	v_mfma_scale_f32_16x16x128_f8f6f4 v[44:47], v[0:7], v[162:169], v[194:197], v152, v152 op_sel_hi:[0,0,0]
	v_mfma_scale_f32_16x16x128_f8f6f4 v[40:43], v[16:23], v[162:169], v[198:201], v152, v152 op_sel_hi:[0,0,0]
	v_mfma_scale_f32_16x16x128_f8f6f4 v[28:31], v[0:7], v[170:177], v[202:205], v152, v152 op_sel_hi:[0,0,0]
	v_mfma_scale_f32_16x16x128_f8f6f4 v[24:27], v[16:23], v[170:177], v[206:209], v152, v152 op_sel_hi:[0,0,0]
	v_mfma_scale_f32_16x16x128_f8f6f4 v[12:15], v[0:7], v[178:185], v[226:229], v152, v152 op_sel_hi:[0,0,0]
	v_mfma_scale_f32_16x16x128_f8f6f4 v[8:11], v[16:23], v[178:185], v[230:233], v152, v152 op_sel_hi:[0,0,0]
	s_setprio 0
	s_setprio 1
	v_mfma_scale_f32_16x16x128_f8f6f4 v[52:55], v[128:135], v[32:39], v[52:55], v152, v152 op_sel_hi:[0,0,0]
	v_mfma_scale_f32_16x16x128_f8f6f4 v[48:51], v[154:161], v[32:39], v[48:51], v152, v152 op_sel_hi:[0,0,0]
	v_mfma_scale_f32_16x16x128_f8f6f4 v[36:39], v[128:135], v[162:169], v[234:237], v152, v152 op_sel_hi:[0,0,0]
	v_mfma_scale_f32_16x16x128_f8f6f4 v[32:35], v[154:161], v[162:169], v[238:241], v152, v152 op_sel_hi:[0,0,0]
	v_mfma_scale_f32_16x16x128_f8f6f4 v[20:23], v[128:135], v[170:177], v[242:245], v152, v152 op_sel_hi:[0,0,0]
	v_mfma_scale_f32_16x16x128_f8f6f4 v[16:19], v[154:161], v[170:177], v[246:249], v152, v152 op_sel_hi:[0,0,0]
	v_mfma_scale_f32_16x16x128_f8f6f4 v[4:7], v[128:135], v[178:185], v[250:253], v152, v152 op_sel_hi:[0,0,0]
	v_mfma_scale_f32_16x16x128_f8f6f4 v[0:3], v[154:161], v[178:185], v[144:147], v152, v152 op_sel_hi:[0,0,0]
	s_setprio 0
	s_barrier
	s_add_i32 s76, s76, 2
	s_add_u32 s74, s74, 0x100
	s_addc_u32 s75, s75, 0
	s_cmp_gt_u32 s76, 29
	s_mov_b64 s[10:11], s[26:27]
	s_cbranch_scc0 .LBB0_1200
	s_and_b64 vcc, exec, s[36:37]
	s_cbranch_vccz .LBB0_1203
	s_barrier

; #define PG8_WAIT_V(n) asm volatile("s_waitcnt vmcnt(" #n ")" ::: "memory")
; #define PG8_BAR __builtin_amdgcn_s_barrier()
;     ...
;     const int aoff = lds_byte(wr * 64 + fr, fq * 8), boff = lds_byte(wc * 32 + fr, fq * 8);
;     ...
;         PG8_STAGE(PG8_SB(0, 0), cB, voffB); PG8_STAGE(PG8_SB(0, 1), cB + hstep, voffB); PG8_STAGE(PG8_SA(0, 0), cA, voffA); PG8_STAGE(PG8_SA(0, 1), cA + hstepA, voffA);
;         if (wr == 1) PG8_BAR;
;         PG8_WAIT_V(2); PG8_BAR;
;         PG8_STAGE(PG8_SB(1, 0), cB + kstep, voffB); PG8_STAGE(PG8_SA(1, 0), cA + kstep, voffA); PG8_STAGE(PG8_SB(1, 1), cB + hstep + kstep, voffB);
;         PG8_WAIT_V(6); PG8_BAR;
.LBB0_1364:
	s_and_b32 s0, s0, 3
	s_lshl_b32 s65, s5, 6
	s_lshl_b32 s5, s5, 13
	s_lshl_b32 s66, s0, 5
	s_lshl_b32 s7, s0, 12
	s_add_u32 s14, s82, 0x3eb00000
	s_addc_u32 s15, s83, 0
	s_add_u32 s22, s82, 0x46b00000
	s_addc_u32 s23, s83, 0
	s_add_u32 s26, s82, 0x47700000
	s_addc_u32 s27, s83, 0
	s_add_u32 s28, s12, 0x80
	s_addc_u32 s29, s13, 0
	s_add_i32 m0, s37, 0x18000
	s_waitcnt vmcnt(2)
	s_barrier
	global_load_lds_dwordx4 v138, s[28:29]
	s_add_i32 m0, s37, 0x1a000
	v_lshl_add_u64 v[2:3], s[28:29], 0, v[142:143]
	s_add_u32 s28, s10, 0x80
	s_addc_u32 s29, s11, 0
	s_add_i32 s67, s37, 0x8000
	global_load_lds_dwordx4 v[2:3], off
	s_mov_b32 m0, s67
	s_add_i32 s68, s37, 0xa000
	global_load_lds_dwordx4 v136, s[28:29]
	v_lshl_add_u64 v[2:3], s[28:29], 0, v[140:141]
	s_add_u32 s28, s12, 0x100080
	s_mov_b32 m0, s68
	s_addc_u32 s29, s13, 0
	global_load_lds_dwordx4 v[2:3], off
	s_add_i32 m0, s37, 0x1c000
	global_load_lds_dwordx4 v138, s[28:29]
	s_add_i32 m0, s37, 0x1e000
	s_cmpk_lt_u32 s4, 0x100
	global_load_lds_dwordx4 v142, s[28:29]
	v_and_b32_e32 v1, 48, v0
	v_lshlrev_b32_e32 v2, 6, v0
	s_movk_i32 s9, 0x3c0
	v_lshlrev_b32_e32 v0, 2, v0
	s_cselect_b64 s[28:29], -1, 0
	s_lshl_b32 s69, s0, 4
	v_and_or_b32 v1, v2, s9, v1
	v_and_b32_e32 v0, 32, v0
	s_waitcnt vmcnt(6)
	s_cmp_eq_u32 s0, 0
	v_bitop3_b32 v2, v1, s5, v0 bitop3:0xde
	v_bitop3_b32 v162, s7, v1, v0 bitop3:0xf6
	s_cselect_b64 s[30:31], -1, 0
	s_add_i32 s71, 0, 0x10000
	s_add_i32 s72, 0, 0x14000
	v_mov_b64_e32 v[146:147], 0x440
	v_mov_b64_e32 v[148:149], 0x43f
	s_movk_i32 s70, 0x89
	v_add_u32_e32 v163, s71, v162
	v_add_u32_e32 v164, s72, v162
	v_add_u32_e32 v165, 0, v2
	s_mov_b32 s36, 0x3c800000
	s_mov_b32 s73, 0
	s_barrier
	s_branch .LBB0_1367

; #define PG8_WAIT_V(n) asm volatile("s_waitcnt vmcnt(" #n ")" ::: "memory")
; #define PG8_WAIT_L(n) asm volatile("s_waitcnt lgkmcnt(" #n ")" ::: "memory")
; #define PG8_BAR __builtin_amdgcn_s_barrier()
; #define PG8_SCHED __builtin_amdgcn_sched_barrier(0)
;     ...
;             PG8_LDB(B0, 0, 0); PG8_LDB(B1, 0, 1); PG8_SCHED; PG8_LDA(At, 0, 0); PG8_STAGE(PG8_SA(1, 1), a1 + hstepA, voffA);
;             PG8_WAIT_V(8); PG8_WAIT_L(0); PG8_BAR; PG8_MMA(0, 0, At, B0); PG8_MMA(0, 1, At, B1); PG8_BAR; PG8_SCHED;
;             if constexpr (!HALFU) PG8_LDA(At, 0, 1); PG8_STAGE(PG8_SB(0, 0), b2, voffB); PG8_STAGE(PG8_SB(0, 1), b2 + hstep, voffB); PG8_STAGE(PG8_SA(0, 0), a2, voffA);
;             PG8_WAIT_V(8); PG8_WAIT_L(0); PG8_BAR; if constexpr (!HALFU) { PG8_MMA(1, 0, At, B0); PG8_MMA(1, 1, At, B1); } PG8_BAR; PG8_SCHED;
.LBB0_1370:
	ds_read_b128 v[128:131], v163
	ds_read_b128 v[132:135], v163 offset:1024
	ds_read_b128 v[150:153], v163 offset:2048
	ds_read_b128 v[154:157], v163 offset:3072
	ds_read_b128 v[158:161], v164
	ds_read_b128 v[166:169], v164 offset:1024
	ds_read_b128 v[170:173], v164 offset:2048
	ds_read_b128 v[174:177], v164 offset:3072
	s_add_u32 s12, s10, 0x100
	s_addc_u32 s13, s11, 0
	s_cmp_eq_u32 s53, 60
	s_cselect_b32 s50, s7, s12
	s_cselect_b32 s51, s0, s13
	s_cselect_b32 s48, s39, s41
	s_cselect_b32 s49, s9, s52
	s_add_u32 s46, s50, 0x80
	s_addc_u32 s47, s51, 0
	s_add_u32 s10, s10, 0x100080
	s_addc_u32 s11, s11, 0
	s_add_i32 m0, s37, 0xc000
	ds_read_b128 v[178:181], v165
	ds_read_b128 v[182:185], v165 offset:1024
	ds_read_b128 v[186:189], v165 offset:2048
	ds_read_b128 v[190:193], v165 offset:3072
	ds_read_b128 v[194:197], v165 offset:4096
	ds_read_b128 v[198:201], v165 offset:5120
	ds_read_b128 v[202:205], v165 offset:6144
	ds_read_b128 v[206:209], v165 offset:7168
	global_load_lds_dwordx4 v136, s[10:11]
	s_add_i32 m0, s37, 0xe000
	s_nop 0
	global_load_lds_dwordx4 v140, s[10:11]
	s_waitcnt vmcnt(8)
	s_waitcnt lgkmcnt(0)
	s_barrier
	s_setprio 1
	s_waitcnt lgkmcnt(0)
	v_mfma_f32_16x16x32_bf16 v[124:127], v[128:131], v[178:181], v[124:127]
	v_mfma_f32_16x16x32_bf16 v[120:123], v[150:153], v[178:181], v[120:123]
	v_mfma_f32_16x16x32_bf16 v[108:111], v[128:131], v[186:189], v[108:111]
	v_mfma_f32_16x16x32_bf16 v[104:107], v[150:153], v[186:189], v[104:107]
	v_mfma_f32_16x16x32_bf16 v[92:95], v[128:131], v[194:197], v[92:95]
	v_mfma_f32_16x16x32_bf16 v[88:91], v[150:153], v[194:197], v[88:91]
	v_mfma_f32_16x16x32_bf16 v[76:79], v[128:131], v[202:205], v[76:79]
	v_mfma_f32_16x16x32_bf16 v[72:75], v[150:153], v[202:205], v[72:75]
	v_mfma_f32_16x16x32_bf16 v[124:127], v[132:135], v[182:185], v[124:127]
	v_mfma_f32_16x16x32_bf16 v[120:123], v[154:157], v[182:185], v[120:123]
	v_mfma_f32_16x16x32_bf16 v[108:111], v[132:135], v[190:193], v[108:111]
	v_mfma_f32_16x16x32_bf16 v[104:107], v[154:157], v[190:193], v[104:107]
	v_mfma_f32_16x16x32_bf16 v[92:95], v[132:135], v[198:201], v[92:95]
	v_mfma_f32_16x16x32_bf16 v[88:91], v[154:157], v[198:201], v[88:91]
	v_mfma_f32_16x16x32_bf16 v[76:79], v[132:135], v[206:209], v[76:79]
	v_mfma_f32_16x16x32_bf16 v[72:75], v[154:157], v[206:209], v[72:75]
	s_setprio 0
	s_setprio 1
	v_mfma_f32_16x16x32_bf16 v[116:119], v[158:161], v[178:181], v[116:119]
	v_mfma_f32_16x16x32_bf16 v[112:115], v[170:173], v[178:181], v[112:115]
	v_mfma_f32_16x16x32_bf16 v[100:103], v[158:161], v[186:189], v[100:103]
	v_mfma_f32_16x16x32_bf16 v[96:99], v[170:173], v[186:189], v[96:99]
	v_mfma_f32_16x16x32_bf16 v[84:87], v[158:161], v[194:197], v[84:87]
	v_mfma_f32_16x16x32_bf16 v[80:83], v[170:173], v[194:197], v[80:83]
	v_mfma_f32_16x16x32_bf16 v[68:71], v[158:161], v[202:205], v[68:71]
	v_mfma_f32_16x16x32_bf16 v[64:67], v[170:173], v[202:205], v[64:67]
	v_mfma_f32_16x16x32_bf16 v[116:119], v[166:169], v[182:185], v[116:119]
	v_mfma_f32_16x16x32_bf16 v[112:115], v[174:177], v[182:185], v[112:115]
	v_mfma_f32_16x16x32_bf16 v[100:103], v[166:169], v[190:193], v[100:103]
	v_mfma_f32_16x16x32_bf16 v[96:99], v[174:177], v[190:193], v[96:99]
	v_mfma_f32_16x16x32_bf16 v[84:87], v[166:169], v[198:201], v[84:87]
	v_mfma_f32_16x16x32_bf16 v[80:83], v[174:177], v[198:201], v[80:83]
	v_mfma_f32_16x16x32_bf16 v[68:71], v[166:169], v[206:209], v[68:71]
	v_mfma_f32_16x16x32_bf16 v[64:67], v[174:177], v[206:209], v[64:67]
	s_setprio 0
	s_barrier
	s_add_i32 s10, s71, s21
	s_mov_b32 m0, s10
	ds_read_b128 v[178:181], v165 offset:16384
	ds_read_b128 v[182:185], v165 offset:17408
	ds_read_b128 v[186:189], v165 offset:18432
	ds_read_b128 v[190:193], v165 offset:19456
	ds_read_b128 v[194:197], v165 offset:20480
	ds_read_b128 v[198:201], v165 offset:21504
	ds_read_b128 v[202:205], v165 offset:22528
	ds_read_b128 v[206:209], v165 offset:23552
	global_load_lds_dwordx4 v138, s[48:49]
	s_add_i32 m0, s10, 0x2000
	s_add_u32 s10, s48, 0x100000
	s_addc_u32 s11, s49, 0
	s_add_i32 s54, s72, s21
	global_load_lds_dwordx4 v142, s[48:49]
	s_mov_b32 m0, s54
	s_nop 0
	global_load_lds_dwordx4 v138, s[10:11]
	s_add_i32 m0, s54, 0x2000
	s_nop 0
	global_load_lds_dwordx4 v142, s[10:11]
	s_mov_b32 m0, s37
	s_nop 0
	global_load_lds_dwordx4 v136, s[50:51]
	s_mov_b32 m0, s62
	s_nop 0
	global_load_lds_dwordx4 v140, s[50:51]
	s_waitcnt vmcnt(8)
	s_waitcnt lgkmcnt(0)
	s_barrier
	s_setprio 1
	s_waitcnt lgkmcnt(0)
	v_mfma_f32_16x16x32_bf16 v[60:63], v[128:131], v[178:181], v[60:63]
	v_mfma_f32_16x16x32_bf16 v[56:59], v[150:153], v[178:181], v[56:59]
	v_mfma_f32_16x16x32_bf16 v[44:47], v[128:131], v[186:189], v[44:47]
	v_mfma_f32_16x16x32_bf16 v[40:43], v[150:153], v[186:189], v[40:43]
	v_mfma_f32_16x16x32_bf16 v[28:31], v[128:131], v[194:197], v[28:31]
	v_mfma_f32_16x16x32_bf16 v[24:27], v[150:153], v[194:197], v[24:27]
	v_mfma_f32_16x16x32_bf16 v[12:15], v[128:131], v[202:205], v[12:15]
	v_mfma_f32_16x16x32_bf16 v[8:11], v[150:153], v[202:205], v[8:11]
	v_mfma_f32_16x16x32_bf16 v[60:63], v[132:135], v[182:185], v[60:63]
	v_mfma_f32_16x16x32_bf16 v[56:59], v[154:157], v[182:185], v[56:59]
	v_mfma_f32_16x16x32_bf16 v[44:47], v[132:135], v[190:193], v[44:47]
	v_mfma_f32_16x16x32_bf16 v[40:43], v[154:157], v[190:193], v[40:43]
	v_mfma_f32_16x16x32_bf16 v[28:31], v[132:135], v[198:201], v[28:31]
	v_mfma_f32_16x16x32_bf16 v[24:27], v[154:157], v[198:201], v[24:27]
	v_mfma_f32_16x16x32_bf16 v[12:15], v[132:135], v[206:209], v[12:15]
	v_mfma_f32_16x16x32_bf16 v[8:11], v[154:157], v[206:209], v[8:11]
	s_setprio 0
	s_setprio 1
	v_mfma_f32_16x16x32_bf16 v[52:55], v[158:161], v[178:181], v[52:55]
	v_mfma_f32_16x16x32_bf16 v[48:51], v[170:173], v[178:181], v[48:51]
	v_mfma_f32_16x16x32_bf16 v[36:39], v[158:161], v[186:189], v[36:39]
	v_mfma_f32_16x16x32_bf16 v[32:35], v[170:173], v[186:189], v[32:35]
	v_mfma_f32_16x16x32_bf16 v[20:23], v[158:161], v[194:197], v[20:23]
	v_mfma_f32_16x16x32_bf16 v[16:19], v[170:173], v[194:197], v[16:19]
	v_mfma_f32_16x16x32_bf16 v[4:7], v[158:161], v[202:205], v[4:7]
	v_mfma_f32_16x16x32_bf16 v[0:3], v[170:173], v[202:205], v[0:3]
	v_mfma_f32_16x16x32_bf16 v[52:55], v[166:169], v[182:185], v[52:55]
	v_mfma_f32_16x16x32_bf16 v[48:51], v[174:177], v[182:185], v[48:51]
	v_mfma_f32_16x16x32_bf16 v[36:39], v[166:169], v[190:193], v[36:39]
	v_mfma_f32_16x16x32_bf16 v[32:35], v[174:177], v[190:193], v[32:35]
	v_mfma_f32_16x16x32_bf16 v[20:23], v[166:169], v[198:201], v[20:23]
	v_mfma_f32_16x16x32_bf16 v[16:19], v[174:177], v[198:201], v[16:19]
	v_mfma_f32_16x16x32_bf16 v[4:7], v[166:169], v[206:209], v[4:7]
	v_mfma_f32_16x16x32_bf16 v[0:3], v[174:177], v[206:209], v[0:3]
	s_setprio 0
	s_barrier
; #define PG8_WAIT_V(n) asm volatile("s_waitcnt vmcnt(" #n ")" ::: "memory")
; #define PG8_WAIT_L(n) asm volatile("s_waitcnt lgkmcnt(" #n ")" ::: "memory")
; #define PG8_BAR __builtin_amdgcn_s_barrier()
; #define PG8_SCHED __builtin_amdgcn_sched_barrier(0)
;     ...
;         for (int t = 0; t < nt; t += 2) {
;             const bool last = (t == nt - 2);
;             const char* a1 = cA + (size_t)(t + 1) * kstep;
;             const char* a2 = last ? nA : cA + (size_t)(t + 2) * kstep; const char* b2 = last ? nB : cB + (size_t)(t + 2) * kstep;
;             const char* a3 = a2 + kstep; const char* b3 = b2 + kstep;
;     ...
;             PG8_LDB(B0, 1, 0); PG8_LDB(B1, 1, 1); PG8_SCHED; PG8_LDA(At, 1, 0); PG8_STAGE(PG8_SA(0, 1), a2 + hstepA, voffA);
;             PG8_WAIT_V(8); PG8_WAIT_L(0); PG8_BAR; PG8_MMA(0, 0, At, B0); PG8_MMA(0, 1, At, B1); PG8_BAR; PG8_SCHED;
;             if constexpr (!HALFU) PG8_LDA(At, 1, 1); PG8_STAGE(PG8_SB(1, 0), b3, voffB); PG8_STAGE(PG8_SB(1, 1), b3 + hstep, voffB); PG8_STAGE(PG8_SA(1, 0), a3, voffA);
;             PG8_WAIT_V(8); PG8_WAIT_L(0); PG8_BAR; if constexpr (!HALFU) { PG8_MMA(1, 0, At, B0); PG8_MMA(1, 1, At, B1); } PG8_BAR; PG8_SCHED;
	s_add_i32 s54, 0, 0x18000
	v_add_u32_e32 v144, s54, v162
	s_add_i32 s55, 0, 0x1c000
	ds_read_b128 v[128:131], v144
	ds_read_b128 v[132:135], v144 offset:1024
	ds_read_b128 v[150:153], v144 offset:2048
	ds_read_b128 v[154:157], v144 offset:3072
	v_add_u32_e32 v144, s55, v162
	ds_read_b128 v[158:161], v144
	ds_read_b128 v[166:169], v144 offset:1024
	ds_read_b128 v[170:173], v144 offset:2048
	ds_read_b128 v[174:177], v144 offset:3072
	s_add_u32 s10, s50, 0x100000
	s_addc_u32 s11, s51, 0
	s_mov_b32 m0, s63
	ds_read_b128 v[178:181], v165 offset:32768
	ds_read_b128 v[182:185], v165 offset:33792
	ds_read_b128 v[186:189], v165 offset:34816
	ds_read_b128 v[190:193], v165 offset:35840
	ds_read_b128 v[194:197], v165 offset:36864
	ds_read_b128 v[198:201], v165 offset:37888
	ds_read_b128 v[202:205], v165 offset:38912
	ds_read_b128 v[206:209], v165 offset:39936
	global_load_lds_dwordx4 v136, s[10:11]
	s_mov_b32 m0, s64
	s_nop 0
	global_load_lds_dwordx4 v140, s[10:11]
	s_waitcnt vmcnt(8)
	s_waitcnt lgkmcnt(0)
	s_barrier
	s_setprio 1
	s_waitcnt lgkmcnt(0)
	v_mfma_f32_16x16x32_bf16 v[124:127], v[128:131], v[178:181], v[124:127]
	v_mfma_f32_16x16x32_bf16 v[120:123], v[150:153], v[178:181], v[120:123]
	v_mfma_f32_16x16x32_bf16 v[108:111], v[128:131], v[186:189], v[108:111]
	v_mfma_f32_16x16x32_bf16 v[104:107], v[150:153], v[186:189], v[104:107]
	v_mfma_f32_16x16x32_bf16 v[92:95], v[128:131], v[194:197], v[92:95]
	v_mfma_f32_16x16x32_bf16 v[88:91], v[150:153], v[194:197], v[88:91]
	v_mfma_f32_16x16x32_bf16 v[76:79], v[128:131], v[202:205], v[76:79]
	v_mfma_f32_16x16x32_bf16 v[72:75], v[150:153], v[202:205], v[72:75]
	v_mfma_f32_16x16x32_bf16 v[124:127], v[132:135], v[182:185], v[124:127]
	v_mfma_f32_16x16x32_bf16 v[120:123], v[154:157], v[182:185], v[120:123]
	v_mfma_f32_16x16x32_bf16 v[108:111], v[132:135], v[190:193], v[108:111]
	v_mfma_f32_16x16x32_bf16 v[104:107], v[154:157], v[190:193], v[104:107]
	v_mfma_f32_16x16x32_bf16 v[92:95], v[132:135], v[198:201], v[92:95]
	v_mfma_f32_16x16x32_bf16 v[88:91], v[154:157], v[198:201], v[88:91]
	v_mfma_f32_16x16x32_bf16 v[76:79], v[132:135], v[206:209], v[76:79]
	v_mfma_f32_16x16x32_bf16 v[72:75], v[154:157], v[206:209], v[72:75]
	s_setprio 0
	s_setprio 1
	v_mfma_f32_16x16x32_bf16 v[116:119], v[158:161], v[178:181], v[116:119]
	v_mfma_f32_16x16x32_bf16 v[112:115], v[170:173], v[178:181], v[112:115]
	v_mfma_f32_16x16x32_bf16 v[100:103], v[158:161], v[186:189], v[100:103]
	v_mfma_f32_16x16x32_bf16 v[96:99], v[170:173], v[186:189], v[96:99]
	v_mfma_f32_16x16x32_bf16 v[84:87], v[158:161], v[194:197], v[84:87]
	v_mfma_f32_16x16x32_bf16 v[80:83], v[170:173], v[194:197], v[80:83]
	v_mfma_f32_16x16x32_bf16 v[68:71], v[158:161], v[202:205], v[68:71]
	v_mfma_f32_16x16x32_bf16 v[64:67], v[170:173], v[202:205], v[64:67]
	v_mfma_f32_16x16x32_bf16 v[116:119], v[166:169], v[182:185], v[116:119]
	v_mfma_f32_16x16x32_bf16 v[112:115], v[174:177], v[182:185], v[112:115]
	v_mfma_f32_16x16x32_bf16 v[100:103], v[166:169], v[190:193], v[100:103]
	v_mfma_f32_16x16x32_bf16 v[96:99], v[174:177], v[190:193], v[96:99]
	v_mfma_f32_16x16x32_bf16 v[84:87], v[166:169], v[198:201], v[84:87]
	v_mfma_f32_16x16x32_bf16 v[80:83], v[174:177], v[198:201], v[80:83]
	v_mfma_f32_16x16x32_bf16 v[68:71], v[166:169], v[206:209], v[68:71]
	v_mfma_f32_16x16x32_bf16 v[64:67], v[174:177], v[206:209], v[64:67]
	s_setprio 0
	s_barrier
	s_add_u32 s10, s48, 0x80
	s_addc_u32 s11, s49, 0
	s_add_i32 s50, s54, s21
	s_mov_b32 m0, s50
	ds_read_b128 v[178:181], v165 offset:49152
	ds_read_b128 v[182:185], v165 offset:50176
	ds_read_b128 v[186:189], v165 offset:51200
	ds_read_b128 v[190:193], v165 offset:52224
	ds_read_b128 v[194:197], v165 offset:53248
	ds_read_b128 v[198:201], v165 offset:54272
	ds_read_b128 v[202:205], v165 offset:55296
	ds_read_b128 v[206:209], v165 offset:56320
	global_load_lds_dwordx4 v138, s[10:11]
	s_add_i32 m0, s50, 0x2000
	v_lshl_add_u64 v[210:211], s[10:11], 0, v[142:143]
	s_add_u32 s10, s48, 0x100080
	s_addc_u32 s11, s49, 0
	s_add_i32 s48, s55, s21
	global_load_lds_dwordx4 v[210:211], off
	s_mov_b32 m0, s48
	s_nop 0
	global_load_lds_dwordx4 v138, s[10:11]
	s_add_i32 m0, s48, 0x2000
	s_nop 0
	global_load_lds_dwordx4 v142, s[10:11]
	s_mov_b32 m0, s67
	s_nop 0
	global_load_lds_dwordx4 v136, s[46:47]
	s_mov_b32 m0, s68
	s_nop 0
	global_load_lds_dwordx4 v140, s[46:47]
	s_waitcnt vmcnt(8)
	s_waitcnt lgkmcnt(0)
	s_barrier
	s_setprio 1
	s_waitcnt lgkmcnt(0)
	v_mfma_f32_16x16x32_bf16 v[60:63], v[128:131], v[178:181], v[60:63]
	v_mfma_f32_16x16x32_bf16 v[56:59], v[150:153], v[178:181], v[56:59]
	v_mfma_f32_16x16x32_bf16 v[44:47], v[128:131], v[186:189], v[44:47]
	v_mfma_f32_16x16x32_bf16 v[40:43], v[150:153], v[186:189], v[40:43]
	v_mfma_f32_16x16x32_bf16 v[28:31], v[128:131], v[194:197], v[28:31]
	v_mfma_f32_16x16x32_bf16 v[24:27], v[150:153], v[194:197], v[24:27]
	v_mfma_f32_16x16x32_bf16 v[12:15], v[128:131], v[202:205], v[12:15]
	v_mfma_f32_16x16x32_bf16 v[8:11], v[150:153], v[202:205], v[8:11]
	v_mfma_f32_16x16x32_bf16 v[60:63], v[132:135], v[182:185], v[60:63]
	v_mfma_f32_16x16x32_bf16 v[56:59], v[154:157], v[182:185], v[56:59]
	v_mfma_f32_16x16x32_bf16 v[44:47], v[132:135], v[190:193], v[44:47]
	v_mfma_f32_16x16x32_bf16 v[40:43], v[154:157], v[190:193], v[40:43]
	v_mfma_f32_16x16x32_bf16 v[28:31], v[132:135], v[198:201], v[28:31]
	v_mfma_f32_16x16x32_bf16 v[24:27], v[154:157], v[198:201], v[24:27]
	v_mfma_f32_16x16x32_bf16 v[12:15], v[132:135], v[206:209], v[12:15]
	v_mfma_f32_16x16x32_bf16 v[8:11], v[154:157], v[206:209], v[8:11]
	s_setprio 0
	s_setprio 1
	v_mfma_f32_16x16x32_bf16 v[52:55], v[158:161], v[178:181], v[52:55]
	v_mfma_f32_16x16x32_bf16 v[48:51], v[170:173], v[178:181], v[48:51]
	v_mfma_f32_16x16x32_bf16 v[36:39], v[158:161], v[186:189], v[36:39]
	v_mfma_f32_16x16x32_bf16 v[32:35], v[170:173], v[186:189], v[32:35]
	v_mfma_f32_16x16x32_bf16 v[20:23], v[158:161], v[194:197], v[20:23]
	v_mfma_f32_16x16x32_bf16 v[16:19], v[170:173], v[194:197], v[16:19]
	v_mfma_f32_16x16x32_bf16 v[4:7], v[158:161], v[202:205], v[4:7]
	v_mfma_f32_16x16x32_bf16 v[0:3], v[170:173], v[202:205], v[0:3]
	v_mfma_f32_16x16x32_bf16 v[52:55], v[166:169], v[182:185], v[52:55]
	v_mfma_f32_16x16x32_bf16 v[48:51], v[174:177], v[182:185], v[48:51]
	v_mfma_f32_16x16x32_bf16 v[36:39], v[166:169], v[190:193], v[36:39]
	v_mfma_f32_16x16x32_bf16 v[32:35], v[174:177], v[190:193], v[32:35]
	v_mfma_f32_16x16x32_bf16 v[20:23], v[166:169], v[198:201], v[20:23]
	v_mfma_f32_16x16x32_bf16 v[16:19], v[174:177], v[198:201], v[16:19]
	v_mfma_f32_16x16x32_bf16 v[4:7], v[166:169], v[206:209], v[4:7]
	v_mfma_f32_16x16x32_bf16 v[0:3], v[174:177], v[206:209], v[0:3]
	s_setprio 0
	s_barrier
	s_add_i32 s53, s53, 2
	s_add_u32 s41, s41, 0x100
	s_addc_u32 s52, s52, 0
	s_cmp_gt_u32 s53, 61
	s_mov_b64 s[10:11], s[12:13]
	s_cbranch_scc0 .LBB0_1370
	s_and_b64 vcc, exec, s[28:29]
	s_cbranch_vccz .LBB0_1373
	s_barrier

; #define PG8_WAIT_V(n) asm volatile("s_waitcnt vmcnt(" #n ")" ::: "memory")
; #define PG8_BAR __builtin_amdgcn_s_barrier()
;     ...
;     const int aoff = lds_byte(wr * 64 + fr, fq * 8), boff = lds_byte(wc * 32 + fr, fq * 8);
;     ...
;         PG8_STAGE(PG8_SB(0, 0), cB, voffB); PG8_STAGE(PG8_SB(0, 1), cB + hstep, voffB); PG8_STAGE(PG8_SA(0, 0), cA, voffA); PG8_STAGE(PG8_SA(0, 1), cA + hstepA, voffA);
;         if (wr == 1) PG8_BAR;
;         PG8_WAIT_V(2); PG8_BAR;
;         PG8_STAGE(PG8_SB(1, 0), cB + kstep, voffB); PG8_STAGE(PG8_SA(1, 0), cA + kstep, voffA); PG8_STAGE(PG8_SB(1, 1), cB + hstep + kstep, voffB);
;         PG8_WAIT_V(6); PG8_BAR;
.LBB0_3548:
	s_lshl_b32 s7, s7, 5
	s_and_b32 s48, s7, 0x60
	s_ashr_i32 s46, s88, 31
	s_lshl_b32 s47, s10, 6
	s_lshl_b32 s12, s10, 13
	s_lshl_b32 s13, s48, 7
	s_add_u32 s10, s26, 0x80
	s_addc_u32 s11, s27, 0
	s_add_i32 m0, s23, 0x18000
	s_waitcnt vmcnt(2)
	s_barrier
	global_load_lds_dwordx4 v128, s[10:11]
	s_add_i32 m0, s23, 0x1a000
	v_lshl_add_u64 v[2:3], s[10:11], 0, v[130:131]
	s_add_u32 s10, s24, 0x80
	s_addc_u32 s11, s25, 0
	s_add_i32 s49, s23, 0x8000
	global_load_lds_dwordx4 v[2:3], off
	s_mov_b32 m0, s49
	s_add_i32 s50, s23, 0xa000
	global_load_lds_dwordx4 v134, s[10:11]
	v_lshl_add_u64 v[2:3], s[10:11], 0, v[132:133]
	s_add_u32 s10, s26, 0x100080
	s_mov_b32 m0, s50
	s_addc_u32 s11, s27, 0
	global_load_lds_dwordx4 v[2:3], off
	s_add_i32 m0, s23, 0x1c000
	global_load_lds_dwordx4 v128, s[10:11]
	s_add_i32 m0, s23, 0x1e000
	s_sext_i32_i16 s53, s4
	global_load_lds_dwordx4 v130, s[10:11]
	v_and_b32_e32 v1, 48, v0
	v_lshlrev_b32_e32 v2, 6, v0
	s_movk_i32 s4, 0x3c0
	v_lshlrev_b32_e32 v0, 2, v0
	s_mov_b32 s7, 0
	v_and_or_b32 v1, v2, s4, v1
	v_and_b32_e32 v0, 32, v0
	s_waitcnt vmcnt(6)
	s_cmpk_lt_u32 s5, 0x100
	v_bitop3_b32 v2, v1, s12, v0 bitop3:0xde
	v_bitop3_b32 v140, s13, v1, v0 bitop3:0xf6
	s_cselect_b64 s[10:11], -1, 0
	v_mov_b64_e32 v[136:137], s[6:7]
	s_add_i32 s6, 0, 0x10000
	s_add_i32 s51, 0, 0x14000
	v_add_u32_e32 v141, s6, v140
	v_add_u32_e32 v142, s51, v140
	v_add_u32_e32 v143, 0, v2
	s_movk_i32 s52, 0x2b00
	s_barrier
	s_branch .LBB0_3551

; #define PG8_WAIT_V(n) asm volatile("s_waitcnt vmcnt(" #n ")" ::: "memory")
; #define PG8_WAIT_L(n) asm volatile("s_waitcnt lgkmcnt(" #n ")" ::: "memory")
; #define PG8_BAR __builtin_amdgcn_s_barrier()
; #define PG8_SCHED __builtin_amdgcn_sched_barrier(0)
;     ...
;             PG8_LDB(B0, 0, 0); PG8_LDB(B1, 0, 1); PG8_SCHED; PG8_LDA(At, 0, 0); PG8_STAGE(PG8_SA(1, 1), a1 + hstepA, voffA);
;             PG8_WAIT_V(8); PG8_WAIT_L(0); PG8_BAR; PG8_MMA(0, 0, At, B0); PG8_MMA(0, 1, At, B1); PG8_BAR; PG8_SCHED;
;             if constexpr (!HALFU) PG8_LDA(At, 0, 1); PG8_STAGE(PG8_SB(0, 0), b2, voffB); PG8_STAGE(PG8_SB(0, 1), b2 + hstep, voffB); PG8_STAGE(PG8_SA(0, 0), a2, voffA);
;             PG8_WAIT_V(8); PG8_WAIT_L(0); PG8_BAR; if constexpr (!HALFU) { PG8_MMA(1, 0, At, B0); PG8_MMA(1, 1, At, B1); } PG8_BAR; PG8_SCHED;
.LBB0_3554:
	ds_read_b128 v[144:147], v141
	ds_read_b128 v[148:151], v141 offset:1024
	ds_read_b128 v[152:155], v141 offset:2048
	ds_read_b128 v[156:159], v141 offset:3072
	ds_read_b128 v[160:163], v142
	ds_read_b128 v[164:167], v142 offset:1024
	ds_read_b128 v[168:171], v142 offset:2048
	ds_read_b128 v[172:175], v142 offset:3072
	s_add_u32 s26, s24, 0x100
	s_addc_u32 s27, s25, 0
	s_cmp_eq_u32 s59, 60
	s_cselect_b32 s36, s54, s26
	s_cselect_b32 s37, s15, s27
	s_cselect_b32 s30, s55, s56
	s_cselect_b32 s31, s13, s57
	s_add_u32 s28, s36, 0x80
	s_addc_u32 s29, s37, 0
	s_add_u32 s24, s24, 0x100080
	s_addc_u32 s25, s25, 0
	s_add_i32 m0, s23, 0xc000
	ds_read_b128 v[176:179], v143
	ds_read_b128 v[180:183], v143 offset:1024
	ds_read_b128 v[184:187], v143 offset:2048
	ds_read_b128 v[188:191], v143 offset:3072
	ds_read_b128 v[192:195], v143 offset:4096
	ds_read_b128 v[196:199], v143 offset:5120
	ds_read_b128 v[200:203], v143 offset:6144
	ds_read_b128 v[204:207], v143 offset:7168
	global_load_lds_dwordx4 v134, s[24:25]
	s_add_i32 m0, s23, 0xe000
	s_nop 0
	global_load_lds_dwordx4 v132, s[24:25]
	s_waitcnt vmcnt(8)
	s_waitcnt lgkmcnt(0)
	s_barrier
	s_setprio 1
	s_waitcnt lgkmcnt(0)
	v_mfma_f32_16x16x32_bf16 v[124:127], v[144:147], v[176:179], v[124:127]
	v_mfma_f32_16x16x32_bf16 v[120:123], v[152:155], v[176:179], v[120:123]
	v_mfma_f32_16x16x32_bf16 v[108:111], v[144:147], v[184:187], v[108:111]
	v_mfma_f32_16x16x32_bf16 v[104:107], v[152:155], v[184:187], v[104:107]
	v_mfma_f32_16x16x32_bf16 v[92:95], v[144:147], v[192:195], v[92:95]
	v_mfma_f32_16x16x32_bf16 v[88:91], v[152:155], v[192:195], v[88:91]
	v_mfma_f32_16x16x32_bf16 v[76:79], v[144:147], v[200:203], v[76:79]
	v_mfma_f32_16x16x32_bf16 v[72:75], v[152:155], v[200:203], v[72:75]
	v_mfma_f32_16x16x32_bf16 v[124:127], v[148:151], v[180:183], v[124:127]
	v_mfma_f32_16x16x32_bf16 v[120:123], v[156:159], v[180:183], v[120:123]
	v_mfma_f32_16x16x32_bf16 v[108:111], v[148:151], v[188:191], v[108:111]
	v_mfma_f32_16x16x32_bf16 v[104:107], v[156:159], v[188:191], v[104:107]
	v_mfma_f32_16x16x32_bf16 v[92:95], v[148:151], v[196:199], v[92:95]
	v_mfma_f32_16x16x32_bf16 v[88:91], v[156:159], v[196:199], v[88:91]
	v_mfma_f32_16x16x32_bf16 v[76:79], v[148:151], v[204:207], v[76:79]
	v_mfma_f32_16x16x32_bf16 v[72:75], v[156:159], v[204:207], v[72:75]
	s_setprio 0
	s_setprio 1
	v_mfma_f32_16x16x32_bf16 v[116:119], v[160:163], v[176:179], v[116:119]
	v_mfma_f32_16x16x32_bf16 v[112:115], v[168:171], v[176:179], v[112:115]
	v_mfma_f32_16x16x32_bf16 v[100:103], v[160:163], v[184:187], v[100:103]
	v_mfma_f32_16x16x32_bf16 v[96:99], v[168:171], v[184:187], v[96:99]
	v_mfma_f32_16x16x32_bf16 v[84:87], v[160:163], v[192:195], v[84:87]
	v_mfma_f32_16x16x32_bf16 v[80:83], v[168:171], v[192:195], v[80:83]
	v_mfma_f32_16x16x32_bf16 v[68:71], v[160:163], v[200:203], v[68:71]
	v_mfma_f32_16x16x32_bf16 v[64:67], v[168:171], v[200:203], v[64:67]
	v_mfma_f32_16x16x32_bf16 v[116:119], v[164:167], v[180:183], v[116:119]
	v_mfma_f32_16x16x32_bf16 v[112:115], v[172:175], v[180:183], v[112:115]
	v_mfma_f32_16x16x32_bf16 v[100:103], v[164:167], v[188:191], v[100:103]
	v_mfma_f32_16x16x32_bf16 v[96:99], v[172:175], v[188:191], v[96:99]
	v_mfma_f32_16x16x32_bf16 v[84:87], v[164:167], v[196:199], v[84:87]
	v_mfma_f32_16x16x32_bf16 v[80:83], v[172:175], v[196:199], v[80:83]
	v_mfma_f32_16x16x32_bf16 v[68:71], v[164:167], v[204:207], v[68:71]
	v_mfma_f32_16x16x32_bf16 v[64:67], v[172:175], v[204:207], v[64:67]
	s_setprio 0
	s_barrier
	s_add_i32 s24, s6, s40
	s_mov_b32 m0, s24
	ds_read_b128 v[176:179], v143 offset:16384
	ds_read_b128 v[180:183], v143 offset:17408
	ds_read_b128 v[184:187], v143 offset:18432
	ds_read_b128 v[188:191], v143 offset:19456
	ds_read_b128 v[192:195], v143 offset:20480
	ds_read_b128 v[196:199], v143 offset:21504
	ds_read_b128 v[200:203], v143 offset:22528
	ds_read_b128 v[204:207], v143 offset:23552
	global_load_lds_dwordx4 v128, s[30:31]
	s_add_i32 m0, s24, 0x2000
	s_add_u32 s24, s30, 0x100000
	s_addc_u32 s25, s31, 0
	s_add_i32 s60, s51, s40
	global_load_lds_dwordx4 v130, s[30:31]
	s_mov_b32 m0, s60
	s_nop 0
	global_load_lds_dwordx4 v128, s[24:25]
	s_add_i32 m0, s60, 0x2000
	s_nop 0
	global_load_lds_dwordx4 v130, s[24:25]
	s_mov_b32 m0, s23
	s_nop 0
	global_load_lds_dwordx4 v134, s[36:37]
	s_mov_b32 m0, s43
	s_nop 0
	global_load_lds_dwordx4 v132, s[36:37]
	s_waitcnt vmcnt(8)
	s_waitcnt lgkmcnt(0)
	s_barrier
	s_setprio 1
	s_waitcnt lgkmcnt(0)
	v_mfma_f32_16x16x32_bf16 v[60:63], v[144:147], v[176:179], v[60:63]
	v_mfma_f32_16x16x32_bf16 v[56:59], v[152:155], v[176:179], v[56:59]
	v_mfma_f32_16x16x32_bf16 v[44:47], v[144:147], v[184:187], v[44:47]
	v_mfma_f32_16x16x32_bf16 v[40:43], v[152:155], v[184:187], v[40:43]
	v_mfma_f32_16x16x32_bf16 v[28:31], v[144:147], v[192:195], v[28:31]
	v_mfma_f32_16x16x32_bf16 v[24:27], v[152:155], v[192:195], v[24:27]
	v_mfma_f32_16x16x32_bf16 v[12:15], v[144:147], v[200:203], v[12:15]
	v_mfma_f32_16x16x32_bf16 v[8:11], v[152:155], v[200:203], v[8:11]
	v_mfma_f32_16x16x32_bf16 v[60:63], v[148:151], v[180:183], v[60:63]
	v_mfma_f32_16x16x32_bf16 v[56:59], v[156:159], v[180:183], v[56:59]
	v_mfma_f32_16x16x32_bf16 v[44:47], v[148:151], v[188:191], v[44:47]
	v_mfma_f32_16x16x32_bf16 v[40:43], v[156:159], v[188:191], v[40:43]
	v_mfma_f32_16x16x32_bf16 v[28:31], v[148:151], v[196:199], v[28:31]
	v_mfma_f32_16x16x32_bf16 v[24:27], v[156:159], v[196:199], v[24:27]
	v_mfma_f32_16x16x32_bf16 v[12:15], v[148:151], v[204:207], v[12:15]
	v_mfma_f32_16x16x32_bf16 v[8:11], v[156:159], v[204:207], v[8:11]
	s_setprio 0
	s_setprio 1
	v_mfma_f32_16x16x32_bf16 v[52:55], v[160:163], v[176:179], v[52:55]
	v_mfma_f32_16x16x32_bf16 v[48:51], v[168:171], v[176:179], v[48:51]
	v_mfma_f32_16x16x32_bf16 v[36:39], v[160:163], v[184:187], v[36:39]
	v_mfma_f32_16x16x32_bf16 v[32:35], v[168:171], v[184:187], v[32:35]
	v_mfma_f32_16x16x32_bf16 v[20:23], v[160:163], v[192:195], v[20:23]
	v_mfma_f32_16x16x32_bf16 v[16:19], v[168:171], v[192:195], v[16:19]
	v_mfma_f32_16x16x32_bf16 v[4:7], v[160:163], v[200:203], v[4:7]
	v_mfma_f32_16x16x32_bf16 v[0:3], v[168:171], v[200:203], v[0:3]
	v_mfma_f32_16x16x32_bf16 v[52:55], v[164:167], v[180:183], v[52:55]
	v_mfma_f32_16x16x32_bf16 v[48:51], v[172:175], v[180:183], v[48:51]
	v_mfma_f32_16x16x32_bf16 v[36:39], v[164:167], v[188:191], v[36:39]
	v_mfma_f32_16x16x32_bf16 v[32:35], v[172:175], v[188:191], v[32:35]
	v_mfma_f32_16x16x32_bf16 v[20:23], v[164:167], v[196:199], v[20:23]
	v_mfma_f32_16x16x32_bf16 v[16:19], v[172:175], v[196:199], v[16:19]
	v_mfma_f32_16x16x32_bf16 v[4:7], v[164:167], v[204:207], v[4:7]
	v_mfma_f32_16x16x32_bf16 v[0:3], v[172:175], v[204:207], v[0:3]
	s_setprio 0
	s_barrier
; #define PG8_WAIT_V(n) asm volatile("s_waitcnt vmcnt(" #n ")" ::: "memory")
; #define PG8_WAIT_L(n) asm volatile("s_waitcnt lgkmcnt(" #n ")" ::: "memory")
; #define PG8_BAR __builtin_amdgcn_s_barrier()
; #define PG8_SCHED __builtin_amdgcn_sched_barrier(0)
;     ...
;         for (int t = 0; t < nt; t += 2) {
;             const bool last = (t == nt - 2);
;             const char* a1 = cA + (size_t)(t + 1) * kstep;
;             const char* a2 = last ? nA : cA + (size_t)(t + 2) * kstep; const char* b2 = last ? nB : cB + (size_t)(t + 2) * kstep;
;             const char* a3 = a2 + kstep; const char* b3 = b2 + kstep;
;     ...
;             PG8_LDB(B0, 1, 0); PG8_LDB(B1, 1, 1); PG8_SCHED; PG8_LDA(At, 1, 0); PG8_STAGE(PG8_SA(0, 1), a2 + hstepA, voffA);
;             PG8_WAIT_V(8); PG8_WAIT_L(0); PG8_BAR; PG8_MMA(0, 0, At, B0); PG8_MMA(0, 1, At, B1); PG8_BAR; PG8_SCHED;
;             if constexpr (!HALFU) PG8_LDA(At, 1, 1); PG8_STAGE(PG8_SB(1, 0), b3, voffB); PG8_STAGE(PG8_SB(1, 1), b3 + hstep, voffB); PG8_STAGE(PG8_SA(1, 0), a3, voffA);
;             PG8_WAIT_V(8); PG8_WAIT_L(0); PG8_BAR; if constexpr (!HALFU) { PG8_MMA(1, 0, At, B0); PG8_MMA(1, 1, At, B1); } PG8_BAR; PG8_SCHED;
	s_add_i32 s60, 0, 0x18000
	v_add_u32_e32 v138, s60, v140
	s_add_i32 s61, 0, 0x1c000
	ds_read_b128 v[144:147], v138
	ds_read_b128 v[148:151], v138 offset:1024
	ds_read_b128 v[152:155], v138 offset:2048
	ds_read_b128 v[156:159], v138 offset:3072
	v_add_u32_e32 v138, s61, v140
	ds_read_b128 v[160:163], v138
	ds_read_b128 v[164:167], v138 offset:1024
	ds_read_b128 v[168:171], v138 offset:2048
	ds_read_b128 v[172:175], v138 offset:3072
	s_add_u32 s24, s36, 0x100000
	s_addc_u32 s25, s37, 0
	s_mov_b32 m0, s44
	ds_read_b128 v[176:179], v143 offset:32768
	ds_read_b128 v[180:183], v143 offset:33792
	ds_read_b128 v[184:187], v143 offset:34816
	ds_read_b128 v[188:191], v143 offset:35840
	ds_read_b128 v[192:195], v143 offset:36864
	ds_read_b128 v[196:199], v143 offset:37888
	ds_read_b128 v[200:203], v143 offset:38912
	ds_read_b128 v[204:207], v143 offset:39936
	global_load_lds_dwordx4 v134, s[24:25]
	s_mov_b32 m0, s45
	s_nop 0
	global_load_lds_dwordx4 v132, s[24:25]
	s_waitcnt vmcnt(8)
	s_waitcnt lgkmcnt(0)
	s_barrier
	s_setprio 1
	s_waitcnt lgkmcnt(0)
	v_mfma_f32_16x16x32_bf16 v[124:127], v[144:147], v[176:179], v[124:127]
	v_mfma_f32_16x16x32_bf16 v[120:123], v[152:155], v[176:179], v[120:123]
	v_mfma_f32_16x16x32_bf16 v[108:111], v[144:147], v[184:187], v[108:111]
	v_mfma_f32_16x16x32_bf16 v[104:107], v[152:155], v[184:187], v[104:107]
	v_mfma_f32_16x16x32_bf16 v[92:95], v[144:147], v[192:195], v[92:95]
	v_mfma_f32_16x16x32_bf16 v[88:91], v[152:155], v[192:195], v[88:91]
	v_mfma_f32_16x16x32_bf16 v[76:79], v[144:147], v[200:203], v[76:79]
	v_mfma_f32_16x16x32_bf16 v[72:75], v[152:155], v[200:203], v[72:75]
	v_mfma_f32_16x16x32_bf16 v[124:127], v[148:151], v[180:183], v[124:127]
	v_mfma_f32_16x16x32_bf16 v[120:123], v[156:159], v[180:183], v[120:123]
	v_mfma_f32_16x16x32_bf16 v[108:111], v[148:151], v[188:191], v[108:111]
	v_mfma_f32_16x16x32_bf16 v[104:107], v[156:159], v[188:191], v[104:107]
	v_mfma_f32_16x16x32_bf16 v[92:95], v[148:151], v[196:199], v[92:95]
	v_mfma_f32_16x16x32_bf16 v[88:91], v[156:159], v[196:199], v[88:91]
	v_mfma_f32_16x16x32_bf16 v[76:79], v[148:151], v[204:207], v[76:79]
	v_mfma_f32_16x16x32_bf16 v[72:75], v[156:159], v[204:207], v[72:75]
	s_setprio 0
	s_setprio 1
	v_mfma_f32_16x16x32_bf16 v[116:119], v[160:163], v[176:179], v[116:119]
	v_mfma_f32_16x16x32_bf16 v[112:115], v[168:171], v[176:179], v[112:115]
	v_mfma_f32_16x16x32_bf16 v[100:103], v[160:163], v[184:187], v[100:103]
	v_mfma_f32_16x16x32_bf16 v[96:99], v[168:171], v[184:187], v[96:99]
	v_mfma_f32_16x16x32_bf16 v[84:87], v[160:163], v[192:195], v[84:87]
	v_mfma_f32_16x16x32_bf16 v[80:83], v[168:171], v[192:195], v[80:83]
	v_mfma_f32_16x16x32_bf16 v[68:71], v[160:163], v[200:203], v[68:71]
	v_mfma_f32_16x16x32_bf16 v[64:67], v[168:171], v[200:203], v[64:67]
	v_mfma_f32_16x16x32_bf16 v[116:119], v[164:167], v[180:183], v[116:119]
	v_mfma_f32_16x16x32_bf16 v[112:115], v[172:175], v[180:183], v[112:115]
	v_mfma_f32_16x16x32_bf16 v[100:103], v[164:167], v[188:191], v[100:103]
	v_mfma_f32_16x16x32_bf16 v[96:99], v[172:175], v[188:191], v[96:99]
	v_mfma_f32_16x16x32_bf16 v[84:87], v[164:167], v[196:199], v[84:87]
	v_mfma_f32_16x16x32_bf16 v[80:83], v[172:175], v[196:199], v[80:83]
	v_mfma_f32_16x16x32_bf16 v[68:71], v[164:167], v[204:207], v[68:71]
	v_mfma_f32_16x16x32_bf16 v[64:67], v[172:175], v[204:207], v[64:67]
	s_setprio 0
	s_barrier
	s_add_u32 s24, s30, 0x80
	s_addc_u32 s25, s31, 0
	s_add_i32 s36, s60, s40
	s_mov_b32 m0, s36
	ds_read_b128 v[176:179], v143 offset:49152
	ds_read_b128 v[180:183], v143 offset:50176
	ds_read_b128 v[184:187], v143 offset:51200
	ds_read_b128 v[188:191], v143 offset:52224
	ds_read_b128 v[192:195], v143 offset:53248
	ds_read_b128 v[196:199], v143 offset:54272
	ds_read_b128 v[200:203], v143 offset:55296
	ds_read_b128 v[204:207], v143 offset:56320
	global_load_lds_dwordx4 v128, s[24:25]
	s_add_i32 m0, s36, 0x2000
	v_lshl_add_u64 v[138:139], s[24:25], 0, v[130:131]
	s_add_u32 s24, s30, 0x100080
	s_addc_u32 s25, s31, 0
	s_add_i32 s30, s61, s40
	global_load_lds_dwordx4 v[138:139], off
	s_mov_b32 m0, s30
	s_nop 0
	global_load_lds_dwordx4 v128, s[24:25]
	s_add_i32 m0, s30, 0x2000
	s_nop 0
	global_load_lds_dwordx4 v130, s[24:25]
	s_mov_b32 m0, s49
	s_nop 0
	global_load_lds_dwordx4 v134, s[28:29]
	s_mov_b32 m0, s50
	s_nop 0
	global_load_lds_dwordx4 v132, s[28:29]
	s_waitcnt vmcnt(8)
	s_waitcnt lgkmcnt(0)
	s_barrier
	s_setprio 1
	s_waitcnt lgkmcnt(0)
	v_mfma_f32_16x16x32_bf16 v[60:63], v[144:147], v[176:179], v[60:63]
	v_mfma_f32_16x16x32_bf16 v[56:59], v[152:155], v[176:179], v[56:59]
	v_mfma_f32_16x16x32_bf16 v[44:47], v[144:147], v[184:187], v[44:47]
	v_mfma_f32_16x16x32_bf16 v[40:43], v[152:155], v[184:187], v[40:43]
	v_mfma_f32_16x16x32_bf16 v[28:31], v[144:147], v[192:195], v[28:31]
	v_mfma_f32_16x16x32_bf16 v[24:27], v[152:155], v[192:195], v[24:27]
	v_mfma_f32_16x16x32_bf16 v[12:15], v[144:147], v[200:203], v[12:15]
	v_mfma_f32_16x16x32_bf16 v[8:11], v[152:155], v[200:203], v[8:11]
	v_mfma_f32_16x16x32_bf16 v[60:63], v[148:151], v[180:183], v[60:63]
	v_mfma_f32_16x16x32_bf16 v[56:59], v[156:159], v[180:183], v[56:59]
	v_mfma_f32_16x16x32_bf16 v[44:47], v[148:151], v[188:191], v[44:47]
	v_mfma_f32_16x16x32_bf16 v[40:43], v[156:159], v[188:191], v[40:43]
	v_mfma_f32_16x16x32_bf16 v[28:31], v[148:151], v[196:199], v[28:31]
	v_mfma_f32_16x16x32_bf16 v[24:27], v[156:159], v[196:199], v[24:27]
	v_mfma_f32_16x16x32_bf16 v[12:15], v[148:151], v[204:207], v[12:15]
	v_mfma_f32_16x16x32_bf16 v[8:11], v[156:159], v[204:207], v[8:11]
	s_setprio 0
	s_setprio 1
	v_mfma_f32_16x16x32_bf16 v[52:55], v[160:163], v[176:179], v[52:55]
	v_mfma_f32_16x16x32_bf16 v[48:51], v[168:171], v[176:179], v[48:51]
	v_mfma_f32_16x16x32_bf16 v[36:39], v[160:163], v[184:187], v[36:39]
	v_mfma_f32_16x16x32_bf16 v[32:35], v[168:171], v[184:187], v[32:35]
	v_mfma_f32_16x16x32_bf16 v[20:23], v[160:163], v[192:195], v[20:23]
	v_mfma_f32_16x16x32_bf16 v[16:19], v[168:171], v[192:195], v[16:19]
	v_mfma_f32_16x16x32_bf16 v[4:7], v[160:163], v[200:203], v[4:7]
	v_mfma_f32_16x16x32_bf16 v[0:3], v[168:171], v[200:203], v[0:3]
	v_mfma_f32_16x16x32_bf16 v[52:55], v[164:167], v[180:183], v[52:55]
	v_mfma_f32_16x16x32_bf16 v[48:51], v[172:175], v[180:183], v[48:51]
	v_mfma_f32_16x16x32_bf16 v[36:39], v[164:167], v[188:191], v[36:39]
	v_mfma_f32_16x16x32_bf16 v[32:35], v[172:175], v[188:191], v[32:35]
	v_mfma_f32_16x16x32_bf16 v[20:23], v[164:167], v[196:199], v[20:23]
	v_mfma_f32_16x16x32_bf16 v[16:19], v[172:175], v[196:199], v[16:19]
	v_mfma_f32_16x16x32_bf16 v[4:7], v[164:167], v[204:207], v[4:7]
	v_mfma_f32_16x16x32_bf16 v[0:3], v[172:175], v[204:207], v[0:3]
	s_setprio 0
	s_barrier
	s_add_i32 s59, s59, 2
	s_add_u32 s56, s56, 0x100
	s_addc_u32 s57, s57, 0
	s_cmp_gt_u32 s59, 61
	s_mov_b64 s[24:25], s[26:27]
	s_cbranch_scc0 .LBB0_3554
	s_and_b64 vcc, exec, s[10:11]
	s_cbranch_vccz .LBB0_3557
	s_barrier

; #define PG8_WAIT_V(n) asm volatile("s_waitcnt vmcnt(" #n ")" ::: "memory")
; #define PG8_WAIT_L(n) asm volatile("s_waitcnt lgkmcnt(" #n ")" ::: "memory")
; #define PG8_BAR __builtin_amdgcn_s_barrier()
; #define PG8_SCHED __builtin_amdgcn_sched_barrier(0)
;     ...
;     Unit cur, nxt; int ui = 0;
;     if (!S.next(0, cur)) return;
;     f32x4 acc[2][2][4][2];
; #pragma unroll
;     for (int a = 0; a < 2; ++a)
; #pragma unroll
;         for (int b = 0; b < 2; ++b)
; #pragma unroll
;             for (int m = 0; m < 4; ++m)
; #pragma unroll
;                 for (int n = 0; n < 2; ++n) acc[a][b][m][n] = (f32x4){0.f, 0.f, 0.f, 0.f};
;     bf16x8 At[4][2], B0[2][2], B1[2][2]; i32x8_t At8[4], B08[2], B18[2];
;     const char* cA = (const char*)g.A + (size_t)cur.pm * tstepA; const char* cB = (const char*)g.Bt + (size_t)cur.pn * tstep;
;     S.a_ready(cur);
;     if constexpr (SP2) {
;         PG8_STAGE(PG8_SB(0, 0), cB, voffB); PG8_STAGE(PG8_SB(0, 1), cB + hstep, voffB); PG8_STAGE(PG8_SA(0, 0), cA, voffA); PG8_STAGE(PG8_SA(0, 1), cA + hstepA, voffA);
;         if (wr == 1) PG8_BAR;
;         PG8_WAIT_V(2); PG8_BAR;
;         PG8_STAGE(PG8_SB(1, 0), cB + kstep, voffB); PG8_STAGE(PG8_SA(1, 0), cA + kstep, voffA); PG8_STAGE(PG8_SB(1, 1), cB + hstep + kstep, voffB);
;         PG8_WAIT_V(6); PG8_BAR;
;     ...
;             PG8_LDB(B0, 0, 0); PG8_LDB(B1, 0, 1); PG8_SCHED; PG8_LDA(At, 0, 0); PG8_STAGE(PG8_SA(1, 1), a1 + hstepA, voffA);
;             PG8_WAIT_V(8); PG8_WAIT_L(0); PG8_BAR; PG8_MMA(0, 0, At, B0); PG8_MMA(0, 1, At, B1); PG8_BAR; PG8_SCHED;
.LBB0_3565:
	v_and_b32_e32 v2, 48, v1
	v_lshlrev_b32_e32 v3, 6, v1
	s_movk_i32 s18, 0x3c0
	s_lshl_b32 s6, s6, 5
	v_and_or_b32 v2, v3, s18, v2
	s_and_b32 s18, s6, 0x60
	s_lshl_b32 s15, s7, 6
	s_lshl_b32 s7, s7, 13
	s_lshl_b32 s6, s18, 7
	v_lshlrev_b32_e32 v1, 2, v1
	s_add_u32 s20, s4, 0x80
	v_and_b32_e32 v1, 32, v1
	s_addc_u32 s21, s5, 0
	v_bitop3_b32 v4, v2, s7, v1 bitop3:0xde
	v_bitop3_b32 v5, s6, v2, v1 bitop3:0xf6
	s_add_i32 m0, s3, 0x18000
	s_waitcnt vmcnt(2)
	s_barrier
	s_mov_b64 s[6:7], 0x80
	global_load_lds_dwordx4 v64, s[20:21]
	s_add_i32 m0, s3, 0x1a000
	s_add_i32 s19, s3, 0x8000
	global_load_lds_dwordx4 v66, s[20:21]
	v_lshl_add_u64 v[2:3], v[74:75], 0, s[6:7]
	s_mov_b32 m0, s19
	v_readfirstlane_b32 s21, v3
	v_readfirstlane_b32 s20, v2
	v_add_u32_e32 v0, s11, v0
	v_ashrrev_i32_e32 v1, 31, v0
	global_load_lds_dwordx4 v70, s[20:21]
	v_lshl_add_u64 v[2:3], s[20:21], 0, v[68:69]
	s_add_i32 s20, s3, 0xa000
	s_add_u32 s22, s4, 0x100080
	s_mov_b32 m0, s20
	s_addc_u32 s23, s5, 0
	global_load_lds_dwordx4 v[2:3], off
	s_add_i32 m0, s3, 0x1c000
	global_load_lds_dwordx4 v64, s[22:23]
	s_add_i32 m0, s3, 0x1e000
	s_add_u32 s8, s82, s8
	global_load_lds_dwordx4 v66, s[22:23]
	v_lshlrev_b64 v[0:1], 20, v[0:1]
	s_addc_u32 s9, s83, s9
	v_lshl_add_u64 v[0:1], s[82:83], 0, v[0:1]
	s_mov_b64 s[22:23], 0x1ab00000
	s_add_u32 s21, s8, 0x7b00100
	s_waitcnt vmcnt(6)
	v_lshl_add_u64 v[76:77], v[0:1], 0, s[22:23]
	s_addc_u32 s22, s9, 0
	s_add_i32 s26, 0, 0x10000
	s_add_i32 s28, 0, 0x14000
	s_add_i32 s30, 0, 0x18000
	s_add_i32 s33, 0, 0x1c000
	v_mov_b32_e32 v0, 0
	v_add_u32_e32 v73, s26, v5
	v_add_u32_e32 v80, s28, v5
	s_add_i32 s26, s26, s10
	s_add_i32 s28, s28, s10
	v_add_u32_e32 v82, s30, v5
	v_add_u32_e32 v83, s33, v5
	s_add_i32 s30, s30, s10
	s_add_i32 s33, s33, s10
	s_mov_b32 s23, -2
	s_mov_b64 s[8:9], 0x100
	v_add_u32_e32 v81, 0, v4
	s_add_i32 s24, s3, 0xc000
	s_add_i32 s25, s3, 0xe000
	s_add_i32 s27, s26, 0x2000
	s_add_i32 s29, s28, 0x2000
	s_add_i32 s31, s30, 0x2000
	s_add_i32 s36, s33, 0x2000
	v_mov_b32_e32 v1, v0
	v_mov_b32_e32 v2, v0
	v_mov_b32_e32 v3, v0
	v_mov_b32_e32 v4, v0
	v_mov_b32_e32 v5, v0
	v_mov_b32_e32 v6, v0
	v_mov_b32_e32 v7, v0
	v_mov_b32_e32 v16, v0
	v_mov_b32_e32 v17, v0
	v_mov_b32_e32 v18, v0
	v_mov_b32_e32 v19, v0
	v_mov_b32_e32 v20, v0
	v_mov_b32_e32 v21, v0
	v_mov_b32_e32 v22, v0
	v_mov_b32_e32 v23, v0
	v_mov_b32_e32 v32, v0
	v_mov_b32_e32 v33, v0
	v_mov_b32_e32 v34, v0
	v_mov_b32_e32 v35, v0
	v_mov_b32_e32 v36, v0
	v_mov_b32_e32 v37, v0
	v_mov_b32_e32 v38, v0
	v_mov_b32_e32 v39, v0
	v_mov_b32_e32 v48, v0
	v_mov_b32_e32 v49, v0
	v_mov_b32_e32 v50, v0
	v_mov_b32_e32 v51, v0
	v_mov_b32_e32 v52, v0
	v_mov_b32_e32 v53, v0
	v_mov_b32_e32 v54, v0
	v_mov_b32_e32 v55, v0
	v_mov_b32_e32 v8, v0
	v_mov_b32_e32 v9, v0
	v_mov_b32_e32 v10, v0
	v_mov_b32_e32 v11, v0
	v_mov_b32_e32 v12, v0
	v_mov_b32_e32 v13, v0
	v_mov_b32_e32 v14, v0
	v_mov_b32_e32 v15, v0
	v_mov_b32_e32 v24, v0
	v_mov_b32_e32 v25, v0
	v_mov_b32_e32 v26, v0
	v_mov_b32_e32 v27, v0
	v_mov_b32_e32 v28, v0
	v_mov_b32_e32 v29, v0
	v_mov_b32_e32 v30, v0
	v_mov_b32_e32 v31, v0
	v_mov_b32_e32 v40, v0
	v_mov_b32_e32 v41, v0
	v_mov_b32_e32 v42, v0
	v_mov_b32_e32 v43, v0
	v_mov_b32_e32 v44, v0
	v_mov_b32_e32 v45, v0
	v_mov_b32_e32 v46, v0
	v_mov_b32_e32 v47, v0
	v_mov_b32_e32 v56, v0
	v_mov_b32_e32 v57, v0
	v_mov_b32_e32 v58, v0
	v_mov_b32_e32 v59, v0
	v_mov_b32_e32 v60, v0
	v_mov_b32_e32 v61, v0
	v_mov_b32_e32 v62, v0
	v_mov_b32_e32 v63, v0
	s_barrier
.LBB0_3566:
	ds_read_b128 v[84:87], v73
	ds_read_b128 v[88:91], v73 offset:1024
	ds_read_b128 v[92:95], v73 offset:2048
	ds_read_b128 v[96:99], v73 offset:3072
	ds_read_b128 v[100:103], v80
	ds_read_b128 v[104:107], v80 offset:1024
	ds_read_b128 v[108:111], v80 offset:2048
	ds_read_b128 v[112:115], v80 offset:3072
	s_cmp_eq_u32 s23, 60
	v_lshl_add_u64 v[78:79], v[76:77], 0, s[8:9]
	s_cselect_b64 vcc, -1, 0
	v_cndmask_b32_e32 v149, v79, v75, vcc
	v_cndmask_b32_e32 v148, v78, v74, vcc
	v_lshl_add_u64 v[76:77], v[76:77], 0, s[6:7]
	s_cselect_b32 s10, s4, s21
	s_cselect_b32 s11, s5, s22
	v_lshl_add_u64 v[150:151], v[148:149], 0, s[6:7]
	v_readfirstlane_b32 s39, v77
	v_readfirstlane_b32 s38, v76
	s_mov_b32 m0, s24
	ds_read_b128 v[116:119], v81
	ds_read_b128 v[120:123], v81 offset:1024
	ds_read_b128 v[124:127], v81 offset:2048
	ds_read_b128 v[128:131], v81 offset:3072
	ds_read_b128 v[132:135], v81 offset:4096
	ds_read_b128 v[136:139], v81 offset:5120
	ds_read_b128 v[140:143], v81 offset:6144
	ds_read_b128 v[144:147], v81 offset:7168
	global_load_lds_dwordx4 v70, s[38:39]
	s_mov_b32 m0, s25
	s_nop 0
	global_load_lds_dwordx4 v68, s[38:39]
	s_waitcnt vmcnt(8)
	s_waitcnt lgkmcnt(0)
	s_barrier
; #define PG8_WAIT_V(n) asm volatile("s_waitcnt vmcnt(" #n ")" ::: "memory")
; #define PG8_WAIT_L(n) asm volatile("s_waitcnt lgkmcnt(" #n ")" ::: "memory")
; #define PG8_BAR __builtin_amdgcn_s_barrier()
; #define PG8_SCHED __builtin_amdgcn_sched_barrier(0)
;     ...
;             PG8_WAIT_V(8); PG8_WAIT_L(0); PG8_BAR; PG8_MMA(0, 0, At, B0); PG8_MMA(0, 1, At, B1); PG8_BAR; PG8_SCHED;
;             if constexpr (!HALFU) PG8_LDA(At, 0, 1); PG8_STAGE(PG8_SB(0, 0), b2, voffB); PG8_STAGE(PG8_SB(0, 1), b2 + hstep, voffB); PG8_STAGE(PG8_SA(0, 0), a2, voffA);
;             PG8_WAIT_V(8); PG8_WAIT_L(0); PG8_BAR; if constexpr (!HALFU) { PG8_MMA(1, 0, At, B0); PG8_MMA(1, 1, At, B1); } PG8_BAR; PG8_SCHED;
;             PG8_LDB(B0, 1, 0); PG8_LDB(B1, 1, 1); PG8_SCHED; PG8_LDA(At, 1, 0); PG8_STAGE(PG8_SA(0, 1), a2 + hstepA, voffA);
;             PG8_WAIT_V(8); PG8_WAIT_L(0); PG8_BAR; PG8_MMA(0, 0, At, B0); PG8_MMA(0, 1, At, B1); PG8_BAR; PG8_SCHED;
;             if constexpr (!HALFU) PG8_LDA(At, 1, 1); PG8_STAGE(PG8_SB(1, 0), b3, voffB); PG8_STAGE(PG8_SB(1, 1), b3 + hstep, voffB); PG8_STAGE(PG8_SA(1, 0), a3, voffA);
;             PG8_WAIT_V(8); PG8_WAIT_L(0); PG8_BAR; if constexpr (!HALFU) { PG8_MMA(1, 0, At, B0); PG8_MMA(1, 1, At, B1); } PG8_BAR; PG8_SCHED;
	s_setprio 1
	s_waitcnt lgkmcnt(0)
	v_mfma_f32_16x16x32_bf16 v[60:63], v[84:87], v[116:119], v[60:63]
	v_mfma_f32_16x16x32_bf16 v[56:59], v[92:95], v[116:119], v[56:59]
	v_mfma_f32_16x16x32_bf16 v[44:47], v[84:87], v[124:127], v[44:47]
	v_mfma_f32_16x16x32_bf16 v[40:43], v[92:95], v[124:127], v[40:43]
	v_mfma_f32_16x16x32_bf16 v[28:31], v[84:87], v[132:135], v[28:31]
	v_mfma_f32_16x16x32_bf16 v[24:27], v[92:95], v[132:135], v[24:27]
	v_mfma_f32_16x16x32_bf16 v[12:15], v[84:87], v[140:143], v[12:15]
	v_mfma_f32_16x16x32_bf16 v[8:11], v[92:95], v[140:143], v[8:11]
	v_mfma_f32_16x16x32_bf16 v[60:63], v[88:91], v[120:123], v[60:63]
	v_mfma_f32_16x16x32_bf16 v[56:59], v[96:99], v[120:123], v[56:59]
	v_mfma_f32_16x16x32_bf16 v[44:47], v[88:91], v[128:131], v[44:47]
	v_mfma_f32_16x16x32_bf16 v[40:43], v[96:99], v[128:131], v[40:43]
	v_mfma_f32_16x16x32_bf16 v[28:31], v[88:91], v[136:139], v[28:31]
	v_mfma_f32_16x16x32_bf16 v[24:27], v[96:99], v[136:139], v[24:27]
	v_mfma_f32_16x16x32_bf16 v[12:15], v[88:91], v[144:147], v[12:15]
	v_mfma_f32_16x16x32_bf16 v[8:11], v[96:99], v[144:147], v[8:11]
	s_setprio 0
	s_setprio 1
	v_mfma_f32_16x16x32_bf16 v[52:55], v[100:103], v[116:119], v[52:55]
	v_mfma_f32_16x16x32_bf16 v[48:51], v[108:111], v[116:119], v[48:51]
	v_mfma_f32_16x16x32_bf16 v[36:39], v[100:103], v[124:127], v[36:39]
	v_mfma_f32_16x16x32_bf16 v[32:35], v[108:111], v[124:127], v[32:35]
	v_mfma_f32_16x16x32_bf16 v[20:23], v[100:103], v[132:135], v[20:23]
	v_mfma_f32_16x16x32_bf16 v[16:19], v[108:111], v[132:135], v[16:19]
	v_mfma_f32_16x16x32_bf16 v[4:7], v[100:103], v[140:143], v[4:7]
	v_mfma_f32_16x16x32_bf16 v[0:3], v[108:111], v[140:143], v[0:3]
	v_mfma_f32_16x16x32_bf16 v[52:55], v[104:107], v[120:123], v[52:55]
	v_mfma_f32_16x16x32_bf16 v[48:51], v[112:115], v[120:123], v[48:51]
	v_mfma_f32_16x16x32_bf16 v[36:39], v[104:107], v[128:131], v[36:39]
	v_mfma_f32_16x16x32_bf16 v[32:35], v[112:115], v[128:131], v[32:35]
	v_mfma_f32_16x16x32_bf16 v[20:23], v[104:107], v[136:139], v[20:23]
	v_mfma_f32_16x16x32_bf16 v[16:19], v[112:115], v[136:139], v[16:19]
	v_mfma_f32_16x16x32_bf16 v[4:7], v[104:107], v[144:147], v[4:7]
	v_mfma_f32_16x16x32_bf16 v[0:3], v[112:115], v[144:147], v[0:3]
	s_setprio 0
	s_barrier
	s_mov_b32 m0, s26
	s_add_u32 s38, s10, 0x100000
	global_load_lds_dwordx4 v64, s[10:11]
	s_mov_b32 m0, s27
	s_addc_u32 s39, s11, 0
	global_load_lds_dwordx4 v66, s[10:11]
	s_mov_b32 m0, s28
	s_nop 0
	global_load_lds_dwordx4 v64, s[38:39]
	v_lshl_add_u64 v[76:77], s[38:39], 0, v[66:67]
	s_mov_b32 m0, s29
	v_readfirstlane_b32 s39, v149
	v_readfirstlane_b32 s38, v148
	global_load_lds_dwordx4 v[76:77], off
	s_nop 0
	s_mov_b32 m0, s3
	global_load_lds_dwordx4 v70, s[38:39]
	s_mov_b32 m0, s13
	s_nop 0
	global_load_lds_dwordx4 v68, s[38:39]
	s_waitcnt vmcnt(8)
	s_waitcnt lgkmcnt(0)
	s_barrier
	s_barrier
	ds_read_b128 v[84:87], v82
	ds_read_b128 v[88:91], v82 offset:1024
	ds_read_b128 v[92:95], v82 offset:2048
	ds_read_b128 v[96:99], v82 offset:3072
	ds_read_b128 v[100:103], v83
	ds_read_b128 v[104:107], v83 offset:1024
	ds_read_b128 v[108:111], v83 offset:2048
	ds_read_b128 v[112:115], v83 offset:3072
	s_mov_b32 m0, s14
	ds_read_b128 v[116:119], v81 offset:32768
	ds_read_b128 v[120:123], v81 offset:33792
	ds_read_b128 v[124:127], v81 offset:34816
	ds_read_b128 v[128:131], v81 offset:35840
	ds_read_b128 v[132:135], v81 offset:36864
	ds_read_b128 v[136:139], v81 offset:37888
	ds_read_b128 v[140:143], v81 offset:38912
	ds_read_b128 v[144:147], v81 offset:39936
	global_load_lds_dwordx4 v70, s[38:39]
	s_mov_b32 m0, s17
	s_nop 0
	global_load_lds_dwordx4 v68, s[38:39]
	s_waitcnt vmcnt(8)
	s_waitcnt lgkmcnt(0)
	s_barrier
	s_setprio 1
	s_waitcnt lgkmcnt(0)
	v_mfma_f32_16x16x32_bf16 v[60:63], v[84:87], v[116:119], v[60:63]
	v_mfma_f32_16x16x32_bf16 v[56:59], v[92:95], v[116:119], v[56:59]
	v_mfma_f32_16x16x32_bf16 v[44:47], v[84:87], v[124:127], v[44:47]
	v_mfma_f32_16x16x32_bf16 v[40:43], v[92:95], v[124:127], v[40:43]
	v_mfma_f32_16x16x32_bf16 v[28:31], v[84:87], v[132:135], v[28:31]
	v_mfma_f32_16x16x32_bf16 v[24:27], v[92:95], v[132:135], v[24:27]
	v_mfma_f32_16x16x32_bf16 v[12:15], v[84:87], v[140:143], v[12:15]
	v_mfma_f32_16x16x32_bf16 v[8:11], v[92:95], v[140:143], v[8:11]
	v_mfma_f32_16x16x32_bf16 v[60:63], v[88:91], v[120:123], v[60:63]
	v_mfma_f32_16x16x32_bf16 v[56:59], v[96:99], v[120:123], v[56:59]
	v_mfma_f32_16x16x32_bf16 v[44:47], v[88:91], v[128:131], v[44:47]
	v_mfma_f32_16x16x32_bf16 v[40:43], v[96:99], v[128:131], v[40:43]
	v_mfma_f32_16x16x32_bf16 v[28:31], v[88:91], v[136:139], v[28:31]
	v_mfma_f32_16x16x32_bf16 v[24:27], v[96:99], v[136:139], v[24:27]
	v_mfma_f32_16x16x32_bf16 v[12:15], v[88:91], v[144:147], v[12:15]
	v_mfma_f32_16x16x32_bf16 v[8:11], v[96:99], v[144:147], v[8:11]
	s_setprio 0
	s_setprio 1
	v_mfma_f32_16x16x32_bf16 v[52:55], v[100:103], v[116:119], v[52:55]
	s_add_u32 s38, s10, 0x80
	s_addc_u32 s39, s11, 0
	v_mfma_f32_16x16x32_bf16 v[48:51], v[108:111], v[116:119], v[48:51]
	v_mfma_f32_16x16x32_bf16 v[36:39], v[100:103], v[124:127], v[36:39]
	v_mfma_f32_16x16x32_bf16 v[32:35], v[108:111], v[124:127], v[32:35]
	v_mfma_f32_16x16x32_bf16 v[20:23], v[100:103], v[132:135], v[20:23]
	v_mfma_f32_16x16x32_bf16 v[16:19], v[108:111], v[132:135], v[16:19]
	v_mfma_f32_16x16x32_bf16 v[4:7], v[100:103], v[140:143], v[4:7]
	v_mfma_f32_16x16x32_bf16 v[0:3], v[108:111], v[140:143], v[0:3]
	v_mfma_f32_16x16x32_bf16 v[52:55], v[104:107], v[120:123], v[52:55]
	v_mfma_f32_16x16x32_bf16 v[48:51], v[112:115], v[120:123], v[48:51]
	v_mfma_f32_16x16x32_bf16 v[36:39], v[104:107], v[128:131], v[36:39]
	v_mfma_f32_16x16x32_bf16 v[32:35], v[112:115], v[128:131], v[32:35]
	v_mfma_f32_16x16x32_bf16 v[20:23], v[104:107], v[136:139], v[20:23]
	v_mfma_f32_16x16x32_bf16 v[16:19], v[112:115], v[136:139], v[16:19]
	v_mfma_f32_16x16x32_bf16 v[4:7], v[104:107], v[144:147], v[4:7]
	v_mfma_f32_16x16x32_bf16 v[0:3], v[112:115], v[144:147], v[0:3]
	s_setprio 0
	s_barrier
	s_mov_b32 m0, s30
	s_add_u32 s10, s10, 0x100080
	global_load_lds_dwordx4 v64, s[38:39]
	s_mov_b32 m0, s31
	s_addc_u32 s11, s11, 0
	global_load_lds_dwordx4 v66, s[38:39]
	s_mov_b32 m0, s33
	s_nop 0
	global_load_lds_dwordx4 v64, s[10:11]
	v_lshl_add_u64 v[76:77], s[10:11], 0, v[66:67]
	s_mov_b32 m0, s36
	v_readfirstlane_b32 s11, v151
	v_readfirstlane_b32 s10, v150
	global_load_lds_dwordx4 v[76:77], off
	s_nop 0
	s_mov_b32 m0, s19
	s_nop 0
	global_load_lds_dwordx4 v70, s[10:11]
	s_mov_b32 m0, s20
	s_nop 0
	global_load_lds_dwordx4 v68, s[10:11]
	s_waitcnt vmcnt(8)
	s_waitcnt lgkmcnt(0)
	s_barrier
	s_barrier
	s_add_i32 s23, s23, 2
	s_add_u32 s21, s21, 0x100
	s_addc_u32 s22, s22, 0
	s_cmp_gt_u32 s23, 61
	v_mov_b64_e32 v[76:77], v[78:79]
	s_cbranch_scc0 .LBB0_3566
	s_cmpk_lt_u32 s12, 0x100
	s_cbranch_scc0 .LBB0_3569
	s_barrier
